# EpiRes: each row-pair's two 16rows x 64B stores fused into two 8rows x 128B stores (DPP row_shl/shr:8 half-row swap, per-lane address deltas via v_mad_i64_i32); counted vmcnt re-derived
# speedup vs baseline: 1.0195x; 1.0029x over previous
; __device__ __forceinline__ unsigned cvt_pk_bf16(float lo, float hi) { f32x2 v = {lo, hi}; bf16x2_t_ b = __builtin_convertvector(v, bf16x2_t_); return __builtin_bit_cast(unsigned, b); }
; __device__ __forceinline__ float bf_lo(unsigned w) { return __uint_as_float(w << 16); }
; __device__ __forceinline__ float bf_hi(unsigned w) { return __uint_as_float(w & 0xffff0000u); }
;     __device__ __forceinline__ void operator()(f32x4 (&acc)[2][2][4][2], const Unit& u, int wr, int wc, int fr, int fq) const {
;         const int t0 = u.pm * 256 + wr * 64 + fr;
;         const int col0 = 256 * u.pn + 32 * wc + 8 * fq;
;         const float* bp0 = first ? ((t0 < NPROMPT) ? xp + (size_t)t0 * 1024 : xs + (size_t)(t0 - NPROMPT) * 1024) : out + (size_t)t0 * 1024;
; #pragma unroll
;         for (int ai = 0; ai < 2; ++ai)
; #pragma unroll
;             for (int m = 0; m < 4; ++m) {
;                 const int j = 128 * ai + 16 * m; float sq = 0.f;
; #pragma unroll
;                 for (int bj = 0; bj < 2; ++bj) {
;                     const size_t o = (size_t)j * 1024 + col0 + 128 * bj;
;                     f32x4 a, b;
;                     if (bb) { const u32x4 w = *(const u32x4*)(xb + (size_t)t0 * 1024 + o);
;                         a = (f32x4){bf_lo(w.x), bf_hi(w.x), bf_lo(w.y), bf_hi(w.y)}; b = (f32x4){bf_lo(w.z), bf_hi(w.z), bf_lo(w.w), bf_hi(w.w)}; }
;                     else { a = *(const f32x4*)(bp0 + o); b = *(const f32x4*)(bp0 + o + 4); }
;                     a = a + acc[ai][bj][m][0]; b = b + acc[ai][bj][m][1];
;                     if (wout) { float* op = out + (size_t)t0 * 1024 + o; *(f32x4*)op = a; *(f32x4*)(op + 4) = b; }
;                     u32x4 w; w.x = cvt_pk_bf16(a.x, a.y); w.y = cvt_pk_bf16(a.z, a.w); w.z = cvt_pk_bf16(b.x, b.y); w.w = cvt_pk_bf16(b.z, b.w);
;                     *(u32x4*)(xb + (size_t)t0 * 1024 + o) = w;
;                     sq += (a.x * a.x + a.y * a.y) + (a.z * a.z + a.w * a.w) + (b.x * b.x + b.y * b.y) + (b.z * b.z + b.w * b.w);
;                 }
;                 sq += __shfl_xor(sq, 16); sq += __shfl_xor(sq, 32);
;                 if (fq == 0) ss[(size_t)(t0 + j) * 16 + 4 * u.pn + wc] = sq;
.LBB0_172:
	v_lshl_add_u32 v138, s56, 8, v140
	v_and_b32_e32 v145, 64, v219
	v_ashrrev_i32_e32 v139, 31, v138
	v_xor_b32_e32 v144, 16, v219
	v_add_u32_e32 v148, 64, v145
	v_lshl_or_b32 v136, s20, 8, v142
	v_lshlrev_b64 v[146:147], 11, v[138:139]
	v_cmp_lt_i32_e32 vcc, v144, v148
	v_ashrrev_i32_e32 v137, 31, v136
	v_lshl_add_u64 v[146:147], s[24:25], 0, v[146:147]
	v_cndmask_b32_e32 v144, v219, v144, vcc
	v_lshlrev_b32_e32 v145, 2, v144
	v_xor_b32_e32 v144, 32, v219
	v_lshl_add_u64 v[136:137], v[136:137], 1, v[146:147]
	v_cmp_lt_i32_e32 vcc, v144, v148
	global_load_dwordx4 v[146:149], v[136:137], off
	s_mov_b32 s101, 0
	global_load_dwordx4 v[154:157], v[136:137], off offset:64
	s_mov_b32 s100, 0x8000
	v_lshl_add_u64 v[240:241], v[136:137], 0, s[100:101]
	global_load_dwordx4 v[158:161], v[240:241], off
	global_load_dwordx4 v[162:165], v[240:241], off offset:64
	s_mov_b32 s100, 0x10000
	v_lshl_add_u64 v[240:241], v[136:137], 0, s[100:101]
	global_load_dwordx4 v[166:169], v[240:241], off
	global_load_dwordx4 v[170:173], v[240:241], off offset:64
	s_mov_b32 s100, 0x18000
	v_lshl_add_u64 v[240:241], v[136:137], 0, s[100:101]
	global_load_dwordx4 v[174:177], v[240:241], off
	global_load_dwordx4 v[178:181], v[240:241], off offset:64
	s_mov_b32 s100, 0x40000
	v_lshl_add_u64 v[240:241], v[136:137], 0, s[100:101]
	global_load_dwordx4 v[182:185], v[240:241], off
	global_load_dwordx4 v[186:189], v[240:241], off offset:64
	s_mov_b32 s100, 0x48000
	v_lshl_add_u64 v[240:241], v[136:137], 0, s[100:101]
	global_load_dwordx4 v[196:199], v[240:241], off
	global_load_dwordx4 v[200:203], v[240:241], off offset:64
	s_mov_b32 s100, 0x50000
	v_lshl_add_u64 v[240:241], v[136:137], 0, s[100:101]
	global_load_dwordx4 v[204:207], v[240:241], off
	global_load_dwordx4 v[208:211], v[240:241], off offset:64
	s_mov_b32 s100, 0x58000
	v_lshl_add_u64 v[240:241], v[136:137], 0, s[100:101]
	global_load_dwordx4 v[212:215], v[240:241], off
	global_load_dwordx4 v[236:239], v[240:241], off offset:64
	v_and_b32_e32 v242, 8, v219
	v_mul_i32_i24_e32 v242, 0xfffff808, v242
	v_add_u32_e32 v243, 0x4000, v242
	v_readlane_b32 s80, v254, 33
	v_cndmask_b32_e32 v144, v219, v144, vcc
	v_lshlrev_b32_e32 v144, 2, v144
	s_lshl_b32 s56, s20, 2
	v_readlane_b32 s81, v254, 34
	s_ashr_i32 s57, s56, 31
	s_waitcnt vmcnt(15)
	v_lshlrev_b32_e32 v150, 16, v146
	v_and_b32_e32 v151, 0xffff0000, v146
	v_lshlrev_b32_e32 v146, 16, v147
	v_and_b32_e32 v147, 0xffff0000, v147
	v_lshlrev_b32_e32 v152, 16, v148
	v_and_b32_e32 v153, 0xffff0000, v148
	v_lshlrev_b32_e32 v148, 16, v149
	v_and_b32_e32 v149, 0xffff0000, v149
	v_pk_add_f32 v[128:129], v[128:129], v[146:147]
	v_pk_add_f32 v[126:127], v[126:127], v[150:151]
	v_pk_add_f32 v[146:147], v[124:125], v[148:149]
	v_pk_add_f32 v[148:149], v[122:123], v[152:153]
	v_cvt_pk_bf16_f32 v122, v126, v127
	v_cvt_pk_bf16_f32 v123, v128, v129
	v_cvt_pk_bf16_f32 v124, v148, v149
	v_cvt_pk_bf16_f32 v125, v146, v147
	v_mov_b64_e32 v[248:249], v[122:123]
	v_mov_b64_e32 v[250:251], v[124:125]
	s_nop 1
	v_mul_f32_e32 v122, v127, v127
	v_mul_f32_e32 v123, v129, v129
	v_fmac_f32_e32 v122, v126, v126
	v_fmac_f32_e32 v123, v128, v128
	v_add_f32_e32 v122, v122, v123
	v_mul_f32_e32 v123, v149, v149
	v_fmac_f32_e32 v123, v148, v148
	v_add_f32_e32 v122, v123, v122
	v_mul_f32_e32 v123, v147, v147
	v_fmac_f32_e32 v123, v146, v146
	v_add_f32_e32 v146, v123, v122
	s_waitcnt vmcnt(14)
	v_mov_b64_e32 v[122:123], v[154:155]
	v_mov_b64_e32 v[124:125], v[156:157]
	v_lshlrev_b32_e32 v126, 16, v122
	v_and_b32_e32 v127, 0xffff0000, v122
	v_lshlrev_b32_e32 v122, 16, v123
	v_and_b32_e32 v123, 0xffff0000, v123
	v_lshlrev_b32_e32 v128, 16, v124
	v_and_b32_e32 v129, 0xffff0000, v124
	v_lshlrev_b32_e32 v124, 16, v125
	v_and_b32_e32 v125, 0xffff0000, v125
	v_pk_add_f32 v[120:121], v[120:121], v[122:123]
	v_pk_add_f32 v[118:119], v[118:119], v[126:127]
	v_pk_add_f32 v[122:123], v[116:117], v[124:125]
	v_pk_add_f32 v[124:125], v[114:115], v[128:129]
	v_cvt_pk_bf16_f32 v114, v118, v119
	v_cvt_pk_bf16_f32 v115, v120, v121
	v_cvt_pk_bf16_f32 v116, v124, v125
	v_cvt_pk_bf16_f32 v117, v122, v123
	v_mov_b64_e32 v[224:225], v[114:115]
	v_mov_b64_e32 v[228:229], v[116:117]
	v_mov_b32_dpp v114, v248 row_shl:8 row_mask:0xf bank_mask:0x3
	v_mov_b32_dpp v115, v249 row_shl:8 row_mask:0xf bank_mask:0x3
	v_mov_b32_dpp v116, v250 row_shl:8 row_mask:0xf bank_mask:0x3
	v_mov_b32_dpp v117, v251 row_shl:8 row_mask:0xf bank_mask:0x3
	v_mov_b32_dpp v248, v224 row_shr:8 row_mask:0xf bank_mask:0xc
	v_mov_b32_dpp v249, v225 row_shr:8 row_mask:0xf bank_mask:0xc
	v_mov_b32_dpp v250, v228 row_shr:8 row_mask:0xf bank_mask:0xc
	v_mov_b32_dpp v251, v229 row_shr:8 row_mask:0xf bank_mask:0xc
	v_mad_i64_i32 v[224:225], s[98:99], v242, 1, v[136:137]
	v_mad_i64_i32 v[228:229], s[98:99], v243, 1, v[136:137]
	global_store_dwordx4 v[224:225], v[248:251], off
	global_store_dwordx4 v[228:229], v[114:117], off
	s_nop 1
	v_mul_f32_e32 v114, v119, v119
	v_mul_f32_e32 v115, v121, v121
	v_fmac_f32_e32 v114, v118, v118
	v_fmac_f32_e32 v115, v120, v120
	v_add_f32_e32 v114, v114, v115
	v_mul_f32_e32 v115, v125, v125
	v_fmac_f32_e32 v115, v124, v124
	v_add_f32_e32 v114, v115, v114
	v_mul_f32_e32 v115, v123, v123
	v_fmac_f32_e32 v115, v122, v122
	v_add_f32_e32 v114, v115, v114
	v_add_f32_e32 v114, v146, v114
	ds_bpermute_b32 v115, v145, v114
	s_waitcnt lgkmcnt(0)
	v_add_f32_e32 v116, v114, v115
	ds_bpermute_b32 v117, v144, v116
	v_lshlrev_b64 v[114:115], 6, v[138:139]
	v_lshl_add_u64 v[114:115], s[80:81], 0, v[114:115]
	s_and_saveexec_b64 s[58:59], s[38:39]
	s_cbranch_execz .LBB0_174
	v_lshl_add_u64 v[118:119], s[56:57], 2, v[114:115]
	s_lshl_b32 s20, s76, 2
	v_lshl_add_u64 v[118:119], v[118:119], 0, s[20:21]
	s_waitcnt lgkmcnt(0)
	v_add_f32_e32 v116, v116, v117
	global_store_dword v[118:119], v116, off
; __device__ __forceinline__ unsigned cvt_pk_bf16(float lo, float hi) { f32x2 v = {lo, hi}; bf16x2_t_ b = __builtin_convertvector(v, bf16x2_t_); return __builtin_bit_cast(unsigned, b); }
; __device__ __forceinline__ float bf_lo(unsigned w) { return __uint_as_float(w << 16); }
; __device__ __forceinline__ float bf_hi(unsigned w) { return __uint_as_float(w & 0xffff0000u); }
;     __device__ __forceinline__ void operator()(f32x4 (&acc)[2][2][4][2], const Unit& u, int wr, int wc, int fr, int fq) const {
;         const int t0 = u.pm * 256 + wr * 64 + fr;
;         const int col0 = 256 * u.pn + 32 * wc + 8 * fq;
;         const float* bp0 = first ? ((t0 < NPROMPT) ? xp + (size_t)t0 * 1024 : xs + (size_t)(t0 - NPROMPT) * 1024) : out + (size_t)t0 * 1024;
; #pragma unroll
;         for (int ai = 0; ai < 2; ++ai)
; #pragma unroll
;             for (int m = 0; m < 4; ++m) {
;                 const int j = 128 * ai + 16 * m; float sq = 0.f;
; #pragma unroll
;                 for (int bj = 0; bj < 2; ++bj) {
;                     const size_t o = (size_t)j * 1024 + col0 + 128 * bj;
;                     f32x4 a, b;
;                     if (bb) { const u32x4 w = *(const u32x4*)(xb + (size_t)t0 * 1024 + o);
;                         a = (f32x4){bf_lo(w.x), bf_hi(w.x), bf_lo(w.y), bf_hi(w.y)}; b = (f32x4){bf_lo(w.z), bf_hi(w.z), bf_lo(w.w), bf_hi(w.w)}; }
;                     else { a = *(const f32x4*)(bp0 + o); b = *(const f32x4*)(bp0 + o + 4); }
;                     a = a + acc[ai][bj][m][0]; b = b + acc[ai][bj][m][1];
;                     if (wout) { float* op = out + (size_t)t0 * 1024 + o; *(f32x4*)op = a; *(f32x4*)(op + 4) = b; }
;                     u32x4 w; w.x = cvt_pk_bf16(a.x, a.y); w.y = cvt_pk_bf16(a.z, a.w); w.z = cvt_pk_bf16(b.x, b.y); w.w = cvt_pk_bf16(b.z, b.w);
;                     *(u32x4*)(xb + (size_t)t0 * 1024 + o) = w;
;                     sq += (a.x * a.x + a.y * a.y) + (a.z * a.z + a.w * a.w) + (b.x * b.x + b.y * b.y) + (b.z * b.z + b.w * b.w);
;                 }
;                 sq += __shfl_xor(sq, 16); sq += __shfl_xor(sq, 32);
;                 if (fq == 0) ss[(size_t)(t0 + j) * 16 + 4 * u.pn + wc] = sq;
.LBB0_174:
	s_or_b64 exec, exec, s[58:59]
	v_add_co_u32_e32 v120, vcc, 0x8000, v136
	s_nop 1
	v_addc_co_u32_e32 v121, vcc, 0, v137, vcc
	s_waitcnt lgkmcnt(0)
	s_waitcnt vmcnt(15)
	v_mov_b64_e32 v[116:117], v[158:159]
	v_mov_b64_e32 v[118:119], v[160:161]
	v_lshlrev_b32_e32 v122, 16, v116
	v_and_b32_e32 v123, 0xffff0000, v116
	v_lshlrev_b32_e32 v116, 16, v117
	v_and_b32_e32 v117, 0xffff0000, v117
	v_lshlrev_b32_e32 v124, 16, v118
	v_and_b32_e32 v125, 0xffff0000, v118
	v_lshlrev_b32_e32 v118, 16, v119
	v_and_b32_e32 v119, 0xffff0000, v119
	v_pk_add_f32 v[112:113], v[112:113], v[116:117]
	v_pk_add_f32 v[110:111], v[110:111], v[122:123]
	v_pk_add_f32 v[116:117], v[108:109], v[118:119]
	v_pk_add_f32 v[118:119], v[106:107], v[124:125]
	v_cvt_pk_bf16_f32 v106, v110, v111
	v_cvt_pk_bf16_f32 v107, v112, v113
	v_cvt_pk_bf16_f32 v108, v118, v119
	v_cvt_pk_bf16_f32 v109, v116, v117
	v_mov_b64_e32 v[248:249], v[106:107]
	v_mov_b64_e32 v[250:251], v[108:109]
	s_nop 1
	v_mul_f32_e32 v106, v111, v111
	v_mul_f32_e32 v107, v113, v113
	v_fmac_f32_e32 v106, v110, v110
	v_fmac_f32_e32 v107, v112, v112
	v_add_f32_e32 v106, v106, v107
	v_mul_f32_e32 v107, v119, v119
	v_fmac_f32_e32 v107, v118, v118
	v_add_f32_e32 v106, v107, v106
	v_mul_f32_e32 v107, v117, v117
	v_fmac_f32_e32 v107, v116, v116
	v_add_f32_e32 v116, v107, v106
	s_waitcnt vmcnt(14)
	v_mov_b64_e32 v[106:107], v[162:163]
	v_mov_b64_e32 v[108:109], v[164:165]
	v_lshlrev_b32_e32 v110, 16, v106
	v_and_b32_e32 v111, 0xffff0000, v106
	v_lshlrev_b32_e32 v106, 16, v107
	v_and_b32_e32 v107, 0xffff0000, v107
	v_lshlrev_b32_e32 v112, 16, v108
	v_and_b32_e32 v113, 0xffff0000, v108
	v_lshlrev_b32_e32 v108, 16, v109
	v_and_b32_e32 v109, 0xffff0000, v109
	v_pk_add_f32 v[104:105], v[104:105], v[106:107]
	v_pk_add_f32 v[102:103], v[102:103], v[110:111]
	v_pk_add_f32 v[106:107], v[100:101], v[108:109]
	v_pk_add_f32 v[108:109], v[98:99], v[112:113]
	v_cvt_pk_bf16_f32 v98, v102, v103
	v_cvt_pk_bf16_f32 v99, v104, v105
	v_cvt_pk_bf16_f32 v100, v108, v109
	v_cvt_pk_bf16_f32 v101, v106, v107
	v_mov_b64_e32 v[224:225], v[98:99]
	v_mov_b64_e32 v[228:229], v[100:101]
	v_mov_b32_dpp v98, v248 row_shl:8 row_mask:0xf bank_mask:0x3
	v_mov_b32_dpp v99, v249 row_shl:8 row_mask:0xf bank_mask:0x3
	v_mov_b32_dpp v100, v250 row_shl:8 row_mask:0xf bank_mask:0x3
	v_mov_b32_dpp v101, v251 row_shl:8 row_mask:0xf bank_mask:0x3
	v_mov_b32_dpp v248, v224 row_shr:8 row_mask:0xf bank_mask:0xc
	v_mov_b32_dpp v249, v225 row_shr:8 row_mask:0xf bank_mask:0xc
	v_mov_b32_dpp v250, v228 row_shr:8 row_mask:0xf bank_mask:0xc
	v_mov_b32_dpp v251, v229 row_shr:8 row_mask:0xf bank_mask:0xc
	v_mad_i64_i32 v[224:225], s[98:99], v242, 1, v[120:121]
	v_mad_i64_i32 v[228:229], s[98:99], v243, 1, v[120:121]
	global_store_dwordx4 v[224:225], v[248:251], off
	global_store_dwordx4 v[228:229], v[98:101], off
	s_nop 1
	v_mul_f32_e32 v98, v103, v103
	v_mul_f32_e32 v99, v105, v105
	v_fmac_f32_e32 v98, v102, v102
	v_fmac_f32_e32 v99, v104, v104
	v_add_f32_e32 v98, v98, v99
	v_mul_f32_e32 v99, v109, v109
	v_fmac_f32_e32 v99, v108, v108
	v_add_f32_e32 v98, v99, v98
	v_mul_f32_e32 v99, v107, v107
	v_fmac_f32_e32 v99, v106, v106
	v_add_f32_e32 v98, v99, v98
	v_add_f32_e32 v98, v116, v98
	ds_bpermute_b32 v99, v145, v98
	s_waitcnt lgkmcnt(0)
	v_add_f32_e32 v98, v98, v99
	ds_bpermute_b32 v99, v144, v98
	s_and_saveexec_b64 s[58:59], s[38:39]
	s_cbranch_execz .LBB0_176
	s_waitcnt lgkmcnt(0)
	v_add_f32_e32 v100, v98, v99
	v_or_b32_e32 v98, 16, v138
	v_ashrrev_i32_e32 v99, 31, v98
	v_lshlrev_b64 v[98:99], 6, v[98:99]
	v_lshl_add_u64 v[98:99], s[80:81], 0, v[98:99]
	v_lshl_add_u64 v[98:99], s[56:57], 2, v[98:99]
	s_lshl_b32 s20, s76, 2
	v_lshl_add_u64 v[98:99], v[98:99], 0, s[20:21]
	global_store_dword v[98:99], v100, off
.LBB0_176:
	s_or_b64 exec, exec, s[58:59]
	v_add_co_u32_e32 v102, vcc, 0x10000, v136
	s_nop 1
	v_addc_co_u32_e32 v103, vcc, 0, v137, vcc
	s_waitcnt lgkmcnt(0)
	s_waitcnt vmcnt(15)
	v_mov_b64_e32 v[98:99], v[166:167]
	v_mov_b64_e32 v[100:101], v[168:169]
	v_lshlrev_b32_e32 v104, 16, v98
	v_and_b32_e32 v105, 0xffff0000, v98
	v_lshlrev_b32_e32 v98, 16, v99
	v_and_b32_e32 v99, 0xffff0000, v99
	v_lshlrev_b32_e32 v106, 16, v100
	v_and_b32_e32 v107, 0xffff0000, v100
	v_lshlrev_b32_e32 v100, 16, v101
	v_and_b32_e32 v101, 0xffff0000, v101
	v_pk_add_f32 v[96:97], v[96:97], v[98:99]
	v_pk_add_f32 v[94:95], v[94:95], v[104:105]
	v_pk_add_f32 v[98:99], v[92:93], v[100:101]
	v_pk_add_f32 v[100:101], v[90:91], v[106:107]
	v_cvt_pk_bf16_f32 v90, v94, v95
	v_cvt_pk_bf16_f32 v91, v96, v97
	v_cvt_pk_bf16_f32 v92, v100, v101
	v_cvt_pk_bf16_f32 v93, v98, v99
	v_mov_b64_e32 v[248:249], v[90:91]
	v_mov_b64_e32 v[250:251], v[92:93]
	s_nop 1
	v_mul_f32_e32 v90, v95, v95
	v_mul_f32_e32 v91, v97, v97
	v_fmac_f32_e32 v90, v94, v94
	v_fmac_f32_e32 v91, v96, v96
	v_add_f32_e32 v90, v90, v91
	v_mul_f32_e32 v91, v101, v101
	v_fmac_f32_e32 v91, v100, v100
	v_add_f32_e32 v90, v91, v90
	v_mul_f32_e32 v91, v99, v99
	v_fmac_f32_e32 v91, v98, v98
	v_add_f32_e32 v98, v91, v90
	s_waitcnt vmcnt(14)
	v_mov_b64_e32 v[90:91], v[170:171]
	v_mov_b64_e32 v[92:93], v[172:173]
	v_lshlrev_b32_e32 v94, 16, v90
	v_and_b32_e32 v95, 0xffff0000, v90
	v_lshlrev_b32_e32 v90, 16, v91
	v_and_b32_e32 v91, 0xffff0000, v91
	v_lshlrev_b32_e32 v96, 16, v92
	v_and_b32_e32 v97, 0xffff0000, v92
	v_lshlrev_b32_e32 v92, 16, v93
	v_and_b32_e32 v93, 0xffff0000, v93
	v_pk_add_f32 v[88:89], v[88:89], v[90:91]
	v_pk_add_f32 v[86:87], v[86:87], v[94:95]
	v_pk_add_f32 v[90:91], v[84:85], v[92:93]
	v_pk_add_f32 v[92:93], v[82:83], v[96:97]
	v_cvt_pk_bf16_f32 v82, v86, v87
	v_cvt_pk_bf16_f32 v83, v88, v89
	v_cvt_pk_bf16_f32 v84, v92, v93
	v_cvt_pk_bf16_f32 v85, v90, v91
	v_mov_b64_e32 v[224:225], v[82:83]
	v_mov_b64_e32 v[228:229], v[84:85]
	v_mov_b32_dpp v82, v248 row_shl:8 row_mask:0xf bank_mask:0x3
	v_mov_b32_dpp v83, v249 row_shl:8 row_mask:0xf bank_mask:0x3
	v_mov_b32_dpp v84, v250 row_shl:8 row_mask:0xf bank_mask:0x3
	v_mov_b32_dpp v85, v251 row_shl:8 row_mask:0xf bank_mask:0x3
	v_mov_b32_dpp v248, v224 row_shr:8 row_mask:0xf bank_mask:0xc
	v_mov_b32_dpp v249, v225 row_shr:8 row_mask:0xf bank_mask:0xc
	v_mov_b32_dpp v250, v228 row_shr:8 row_mask:0xf bank_mask:0xc
	v_mov_b32_dpp v251, v229 row_shr:8 row_mask:0xf bank_mask:0xc
	v_mad_i64_i32 v[224:225], s[98:99], v242, 1, v[102:103]
	v_mad_i64_i32 v[228:229], s[98:99], v243, 1, v[102:103]
	global_store_dwordx4 v[224:225], v[248:251], off
	global_store_dwordx4 v[228:229], v[82:85], off
	s_nop 1
	v_mul_f32_e32 v82, v87, v87
	v_mul_f32_e32 v83, v89, v89
	v_fmac_f32_e32 v82, v86, v86
	v_fmac_f32_e32 v83, v88, v88
	v_add_f32_e32 v82, v82, v83
	v_mul_f32_e32 v83, v93, v93
	v_fmac_f32_e32 v83, v92, v92
	v_add_f32_e32 v82, v83, v82
	v_mul_f32_e32 v83, v91, v91
	v_fmac_f32_e32 v83, v90, v90
	v_add_f32_e32 v82, v83, v82
	v_add_f32_e32 v82, v98, v82
	ds_bpermute_b32 v83, v145, v82
	s_waitcnt lgkmcnt(0)
	v_add_f32_e32 v82, v82, v83
	ds_bpermute_b32 v83, v144, v82
	s_and_saveexec_b64 s[58:59], s[38:39]
	s_movk_i32 s49, 0xc1
	s_cbranch_execz .LBB0_178
; __device__ __forceinline__ unsigned cvt_pk_bf16(float lo, float hi) { f32x2 v = {lo, hi}; bf16x2_t_ b = __builtin_convertvector(v, bf16x2_t_); return __builtin_bit_cast(unsigned, b); }
; __device__ __forceinline__ float bf_lo(unsigned w) { return __uint_as_float(w << 16); }
; __device__ __forceinline__ float bf_hi(unsigned w) { return __uint_as_float(w & 0xffff0000u); }
;     __device__ __forceinline__ void operator()(f32x4 (&acc)[2][2][4][2], const Unit& u, int wr, int wc, int fr, int fq) const {
;         const int t0 = u.pm * 256 + wr * 64 + fr;
;         const int col0 = 256 * u.pn + 32 * wc + 8 * fq;
;         const float* bp0 = first ? ((t0 < NPROMPT) ? xp + (size_t)t0 * 1024 : xs + (size_t)(t0 - NPROMPT) * 1024) : out + (size_t)t0 * 1024;
; #pragma unroll
;         for (int ai = 0; ai < 2; ++ai)
; #pragma unroll
;             for (int m = 0; m < 4; ++m) {
;                 const int j = 128 * ai + 16 * m; float sq = 0.f;
; #pragma unroll
;                 for (int bj = 0; bj < 2; ++bj) {
;                     const size_t o = (size_t)j * 1024 + col0 + 128 * bj;
;                     f32x4 a, b;
;                     if (bb) { const u32x4 w = *(const u32x4*)(xb + (size_t)t0 * 1024 + o);
;                         a = (f32x4){bf_lo(w.x), bf_hi(w.x), bf_lo(w.y), bf_hi(w.y)}; b = (f32x4){bf_lo(w.z), bf_hi(w.z), bf_lo(w.w), bf_hi(w.w)}; }
;                     else { a = *(const f32x4*)(bp0 + o); b = *(const f32x4*)(bp0 + o + 4); }
;                     a = a + acc[ai][bj][m][0]; b = b + acc[ai][bj][m][1];
;                     if (wout) { float* op = out + (size_t)t0 * 1024 + o; *(f32x4*)op = a; *(f32x4*)(op + 4) = b; }
;                     u32x4 w; w.x = cvt_pk_bf16(a.x, a.y); w.y = cvt_pk_bf16(a.z, a.w); w.z = cvt_pk_bf16(b.x, b.y); w.w = cvt_pk_bf16(b.z, b.w);
;                     *(u32x4*)(xb + (size_t)t0 * 1024 + o) = w;
;                     sq += (a.x * a.x + a.y * a.y) + (a.z * a.z + a.w * a.w) + (b.x * b.x + b.y * b.y) + (b.z * b.z + b.w * b.w);
;                 }
;                 sq += __shfl_xor(sq, 16); sq += __shfl_xor(sq, 32);
;                 if (fq == 0) ss[(size_t)(t0 + j) * 16 + 4 * u.pn + wc] = sq;
	s_waitcnt lgkmcnt(0)
	v_add_f32_e32 v84, v82, v83
	v_or_b32_e32 v82, 32, v138
	v_ashrrev_i32_e32 v83, 31, v82
	v_lshlrev_b64 v[82:83], 6, v[82:83]
	v_lshl_add_u64 v[82:83], s[80:81], 0, v[82:83]
	v_lshl_add_u64 v[82:83], s[56:57], 2, v[82:83]
	s_lshl_b32 s20, s76, 2
	v_lshl_add_u64 v[82:83], v[82:83], 0, s[20:21]
	global_store_dword v[82:83], v84, off
.LBB0_178:
	s_or_b64 exec, exec, s[58:59]
	v_add_co_u32_e32 v86, vcc, 0x18000, v136
	s_nop 1
	v_addc_co_u32_e32 v87, vcc, 0, v137, vcc
	s_waitcnt lgkmcnt(0)
	s_waitcnt vmcnt(15)
	v_mov_b64_e32 v[82:83], v[174:175]
	v_mov_b64_e32 v[84:85], v[176:177]
	v_lshlrev_b32_e32 v88, 16, v82
	v_and_b32_e32 v89, 0xffff0000, v82
	v_lshlrev_b32_e32 v82, 16, v83
	v_and_b32_e32 v83, 0xffff0000, v83
	v_lshlrev_b32_e32 v90, 16, v84
	v_and_b32_e32 v91, 0xffff0000, v84
	v_lshlrev_b32_e32 v84, 16, v85
	v_and_b32_e32 v85, 0xffff0000, v85
	v_pk_add_f32 v[80:81], v[80:81], v[82:83]
	v_pk_add_f32 v[78:79], v[78:79], v[88:89]
	v_pk_add_f32 v[82:83], v[76:77], v[84:85]
	v_pk_add_f32 v[84:85], v[74:75], v[90:91]
	v_cvt_pk_bf16_f32 v74, v78, v79
	v_cvt_pk_bf16_f32 v75, v80, v81
	v_cvt_pk_bf16_f32 v76, v84, v85
	v_cvt_pk_bf16_f32 v77, v82, v83
	v_mov_b64_e32 v[248:249], v[74:75]
	v_mov_b64_e32 v[250:251], v[76:77]
	s_nop 1
	v_mul_f32_e32 v74, v79, v79
	v_mul_f32_e32 v75, v81, v81
	v_fmac_f32_e32 v74, v78, v78
	v_fmac_f32_e32 v75, v80, v80
	v_add_f32_e32 v74, v74, v75
	v_mul_f32_e32 v75, v85, v85
	v_fmac_f32_e32 v75, v84, v84
	v_add_f32_e32 v74, v75, v74
	v_mul_f32_e32 v75, v83, v83
	v_fmac_f32_e32 v75, v82, v82
	v_add_f32_e32 v82, v75, v74
	s_waitcnt vmcnt(14)
	v_mov_b64_e32 v[74:75], v[178:179]
	v_mov_b64_e32 v[76:77], v[180:181]
	v_lshlrev_b32_e32 v78, 16, v74
	v_and_b32_e32 v79, 0xffff0000, v74
	v_lshlrev_b32_e32 v74, 16, v75
	v_and_b32_e32 v75, 0xffff0000, v75
	v_lshlrev_b32_e32 v80, 16, v76
	v_and_b32_e32 v81, 0xffff0000, v76
	v_lshlrev_b32_e32 v76, 16, v77
	v_and_b32_e32 v77, 0xffff0000, v77
	v_pk_add_f32 v[72:73], v[72:73], v[74:75]
	v_pk_add_f32 v[70:71], v[70:71], v[78:79]
	v_pk_add_f32 v[74:75], v[68:69], v[76:77]
	v_pk_add_f32 v[76:77], v[66:67], v[80:81]
	v_cvt_pk_bf16_f32 v66, v70, v71
	v_cvt_pk_bf16_f32 v67, v72, v73
	v_cvt_pk_bf16_f32 v68, v76, v77
	v_cvt_pk_bf16_f32 v69, v74, v75
	v_mov_b64_e32 v[224:225], v[66:67]
	v_mov_b64_e32 v[228:229], v[68:69]
	v_mov_b32_dpp v66, v248 row_shl:8 row_mask:0xf bank_mask:0x3
	v_mov_b32_dpp v67, v249 row_shl:8 row_mask:0xf bank_mask:0x3
	v_mov_b32_dpp v68, v250 row_shl:8 row_mask:0xf bank_mask:0x3
	v_mov_b32_dpp v69, v251 row_shl:8 row_mask:0xf bank_mask:0x3
	v_mov_b32_dpp v248, v224 row_shr:8 row_mask:0xf bank_mask:0xc
	v_mov_b32_dpp v249, v225 row_shr:8 row_mask:0xf bank_mask:0xc
	v_mov_b32_dpp v250, v228 row_shr:8 row_mask:0xf bank_mask:0xc
	v_mov_b32_dpp v251, v229 row_shr:8 row_mask:0xf bank_mask:0xc
	v_mad_i64_i32 v[224:225], s[98:99], v242, 1, v[86:87]
	v_mad_i64_i32 v[228:229], s[98:99], v243, 1, v[86:87]
	global_store_dwordx4 v[224:225], v[248:251], off
	global_store_dwordx4 v[228:229], v[66:69], off
	s_nop 1
	v_mul_f32_e32 v66, v71, v71
	v_mul_f32_e32 v67, v73, v73
	v_fmac_f32_e32 v66, v70, v70
	v_fmac_f32_e32 v67, v72, v72
	v_add_f32_e32 v66, v66, v67
	v_mul_f32_e32 v67, v77, v77
	v_fmac_f32_e32 v67, v76, v76
	v_add_f32_e32 v66, v67, v66
	v_mul_f32_e32 v67, v75, v75
	v_fmac_f32_e32 v67, v74, v74
	v_add_f32_e32 v66, v67, v66
	v_add_f32_e32 v66, v82, v66
	ds_bpermute_b32 v67, v145, v66
	s_waitcnt lgkmcnt(0)
	v_add_f32_e32 v66, v66, v67
	ds_bpermute_b32 v67, v144, v66
	s_and_saveexec_b64 s[58:59], s[38:39]
	s_cbranch_execz .LBB0_180
	s_waitcnt lgkmcnt(0)
	v_add_f32_e32 v68, v66, v67
	v_or_b32_e32 v66, 48, v138
	v_ashrrev_i32_e32 v67, 31, v66
	v_lshlrev_b64 v[66:67], 6, v[66:67]
	v_lshl_add_u64 v[66:67], s[80:81], 0, v[66:67]
	v_lshl_add_u64 v[66:67], s[56:57], 2, v[66:67]
	s_lshl_b32 s20, s76, 2
	v_lshl_add_u64 v[66:67], v[66:67], 0, s[20:21]
	global_store_dword v[66:67], v68, off
.LBB0_180:
	s_or_b64 exec, exec, s[58:59]
	v_add_co_u32_e32 v70, vcc, 0x40000, v136
	s_nop 1
	v_addc_co_u32_e32 v71, vcc, 0, v137, vcc
	s_waitcnt lgkmcnt(0)
	s_waitcnt vmcnt(15)
	v_mov_b64_e32 v[66:67], v[182:183]
	v_mov_b64_e32 v[68:69], v[184:185]
	v_lshlrev_b32_e32 v72, 16, v66
	v_and_b32_e32 v73, 0xffff0000, v66
	v_lshlrev_b32_e32 v66, 16, v67
	v_and_b32_e32 v67, 0xffff0000, v67
	v_lshlrev_b32_e32 v74, 16, v68
	v_and_b32_e32 v75, 0xffff0000, v68
	v_lshlrev_b32_e32 v68, 16, v69
	v_and_b32_e32 v69, 0xffff0000, v69
	v_pk_add_f32 v[64:65], v[64:65], v[66:67]
	v_pk_add_f32 v[62:63], v[62:63], v[72:73]
	v_pk_add_f32 v[66:67], v[60:61], v[68:69]
	v_pk_add_f32 v[68:69], v[58:59], v[74:75]
	v_cvt_pk_bf16_f32 v58, v62, v63
	v_cvt_pk_bf16_f32 v59, v64, v65
	v_cvt_pk_bf16_f32 v60, v68, v69
	v_cvt_pk_bf16_f32 v61, v66, v67
	v_mov_b64_e32 v[248:249], v[58:59]
	v_mov_b64_e32 v[250:251], v[60:61]
	s_nop 1
	v_mul_f32_e32 v58, v63, v63
	v_mul_f32_e32 v59, v65, v65
	v_fmac_f32_e32 v58, v62, v62
	v_fmac_f32_e32 v59, v64, v64
	v_add_f32_e32 v58, v58, v59
	v_mul_f32_e32 v59, v69, v69
	v_fmac_f32_e32 v59, v68, v68
	v_add_f32_e32 v58, v59, v58
	v_mul_f32_e32 v59, v67, v67
	v_fmac_f32_e32 v59, v66, v66
	v_add_f32_e32 v66, v59, v58
	s_waitcnt vmcnt(14)
; __device__ __forceinline__ unsigned cvt_pk_bf16(float lo, float hi) { f32x2 v = {lo, hi}; bf16x2_t_ b = __builtin_convertvector(v, bf16x2_t_); return __builtin_bit_cast(unsigned, b); }
; __device__ __forceinline__ float bf_lo(unsigned w) { return __uint_as_float(w << 16); }
; __device__ __forceinline__ float bf_hi(unsigned w) { return __uint_as_float(w & 0xffff0000u); }
;     __device__ __forceinline__ void operator()(f32x4 (&acc)[2][2][4][2], const Unit& u, int wr, int wc, int fr, int fq) const {
;         const int t0 = u.pm * 256 + wr * 64 + fr;
;         const int col0 = 256 * u.pn + 32 * wc + 8 * fq;
;         const float* bp0 = first ? ((t0 < NPROMPT) ? xp + (size_t)t0 * 1024 : xs + (size_t)(t0 - NPROMPT) * 1024) : out + (size_t)t0 * 1024;
; #pragma unroll
;         for (int ai = 0; ai < 2; ++ai)
; #pragma unroll
;             for (int m = 0; m < 4; ++m) {
;                 const int j = 128 * ai + 16 * m; float sq = 0.f;
; #pragma unroll
;                 for (int bj = 0; bj < 2; ++bj) {
;                     const size_t o = (size_t)j * 1024 + col0 + 128 * bj;
;                     f32x4 a, b;
;                     if (bb) { const u32x4 w = *(const u32x4*)(xb + (size_t)t0 * 1024 + o);
;                         a = (f32x4){bf_lo(w.x), bf_hi(w.x), bf_lo(w.y), bf_hi(w.y)}; b = (f32x4){bf_lo(w.z), bf_hi(w.z), bf_lo(w.w), bf_hi(w.w)}; }
;                     else { a = *(const f32x4*)(bp0 + o); b = *(const f32x4*)(bp0 + o + 4); }
;                     a = a + acc[ai][bj][m][0]; b = b + acc[ai][bj][m][1];
;                     if (wout) { float* op = out + (size_t)t0 * 1024 + o; *(f32x4*)op = a; *(f32x4*)(op + 4) = b; }
;                     u32x4 w; w.x = cvt_pk_bf16(a.x, a.y); w.y = cvt_pk_bf16(a.z, a.w); w.z = cvt_pk_bf16(b.x, b.y); w.w = cvt_pk_bf16(b.z, b.w);
;                     *(u32x4*)(xb + (size_t)t0 * 1024 + o) = w;
;                     sq += (a.x * a.x + a.y * a.y) + (a.z * a.z + a.w * a.w) + (b.x * b.x + b.y * b.y) + (b.z * b.z + b.w * b.w);
;                 }
;                 sq += __shfl_xor(sq, 16); sq += __shfl_xor(sq, 32);
;                 if (fq == 0) ss[(size_t)(t0 + j) * 16 + 4 * u.pn + wc] = sq;
	v_mov_b64_e32 v[58:59], v[186:187]
	v_mov_b64_e32 v[60:61], v[188:189]
	v_lshlrev_b32_e32 v62, 16, v58
	v_and_b32_e32 v63, 0xffff0000, v58
	v_lshlrev_b32_e32 v58, 16, v59
	v_and_b32_e32 v59, 0xffff0000, v59
	v_lshlrev_b32_e32 v64, 16, v60
	v_and_b32_e32 v65, 0xffff0000, v60
	v_lshlrev_b32_e32 v60, 16, v61
	v_and_b32_e32 v61, 0xffff0000, v61
	v_pk_add_f32 v[56:57], v[56:57], v[58:59]
	v_pk_add_f32 v[54:55], v[54:55], v[62:63]
	v_pk_add_f32 v[58:59], v[52:53], v[60:61]
	v_pk_add_f32 v[60:61], v[50:51], v[64:65]
	v_cvt_pk_bf16_f32 v50, v54, v55
	v_cvt_pk_bf16_f32 v51, v56, v57
	v_cvt_pk_bf16_f32 v52, v60, v61
	v_cvt_pk_bf16_f32 v53, v58, v59
	v_mov_b64_e32 v[224:225], v[50:51]
	v_mov_b64_e32 v[228:229], v[52:53]
	v_mov_b32_dpp v50, v248 row_shl:8 row_mask:0xf bank_mask:0x3
	v_mov_b32_dpp v51, v249 row_shl:8 row_mask:0xf bank_mask:0x3
	v_mov_b32_dpp v52, v250 row_shl:8 row_mask:0xf bank_mask:0x3
	v_mov_b32_dpp v53, v251 row_shl:8 row_mask:0xf bank_mask:0x3
	v_mov_b32_dpp v248, v224 row_shr:8 row_mask:0xf bank_mask:0xc
	v_mov_b32_dpp v249, v225 row_shr:8 row_mask:0xf bank_mask:0xc
	v_mov_b32_dpp v250, v228 row_shr:8 row_mask:0xf bank_mask:0xc
	v_mov_b32_dpp v251, v229 row_shr:8 row_mask:0xf bank_mask:0xc
	v_mad_i64_i32 v[224:225], s[98:99], v242, 1, v[70:71]
	v_mad_i64_i32 v[228:229], s[98:99], v243, 1, v[70:71]
	global_store_dwordx4 v[224:225], v[248:251], off
	global_store_dwordx4 v[228:229], v[50:53], off
	s_nop 1
	v_mul_f32_e32 v50, v55, v55
	v_mul_f32_e32 v51, v57, v57
	v_fmac_f32_e32 v50, v54, v54
	v_fmac_f32_e32 v51, v56, v56
	v_add_f32_e32 v50, v50, v51
	v_mul_f32_e32 v51, v61, v61
	v_fmac_f32_e32 v51, v60, v60
	v_add_f32_e32 v50, v51, v50
	v_mul_f32_e32 v51, v59, v59
	v_fmac_f32_e32 v51, v58, v58
	v_add_f32_e32 v50, v51, v50
	v_add_f32_e32 v50, v66, v50
	ds_bpermute_b32 v51, v145, v50
	s_waitcnt lgkmcnt(0)
	v_add_f32_e32 v50, v50, v51
	ds_bpermute_b32 v51, v144, v50
	s_and_saveexec_b64 s[58:59], s[38:39]
	s_cbranch_execz .LBB0_182
	s_waitcnt lgkmcnt(0)
	v_add_f32_e32 v52, v50, v51
	v_lshl_add_u64 v[50:51], s[56:57], 2, v[114:115]
	s_lshl_b32 s20, s76, 2
	v_lshl_add_u64 v[50:51], v[50:51], 0, s[20:21]
	v_add_co_u32_e32 v50, vcc, 0x2000, v50
	s_nop 1
	v_addc_co_u32_e32 v51, vcc, 0, v51, vcc
	global_store_dword v[50:51], v52, off
.LBB0_182:
	s_or_b64 exec, exec, s[58:59]
	v_add_co_u32_e32 v54, vcc, 0x48000, v136
	s_nop 1
	v_addc_co_u32_e32 v55, vcc, 0, v137, vcc
	s_waitcnt lgkmcnt(0)
	s_waitcnt vmcnt(15)
	v_mov_b64_e32 v[50:51], v[196:197]
	v_mov_b64_e32 v[52:53], v[198:199]
	v_lshlrev_b32_e32 v56, 16, v50
	v_and_b32_e32 v57, 0xffff0000, v50
	v_lshlrev_b32_e32 v50, 16, v51
	v_and_b32_e32 v51, 0xffff0000, v51
	v_lshlrev_b32_e32 v58, 16, v52
	v_and_b32_e32 v59, 0xffff0000, v52
	v_lshlrev_b32_e32 v52, 16, v53
	v_and_b32_e32 v53, 0xffff0000, v53
	v_pk_add_f32 v[48:49], v[48:49], v[50:51]
	v_pk_add_f32 v[46:47], v[46:47], v[56:57]
	v_pk_add_f32 v[50:51], v[44:45], v[52:53]
	v_pk_add_f32 v[52:53], v[42:43], v[58:59]
	v_cvt_pk_bf16_f32 v42, v46, v47
	v_cvt_pk_bf16_f32 v43, v48, v49
	v_cvt_pk_bf16_f32 v44, v52, v53
	v_cvt_pk_bf16_f32 v45, v50, v51
	v_mov_b64_e32 v[248:249], v[42:43]
	v_mov_b64_e32 v[250:251], v[44:45]
	s_nop 1
	v_mul_f32_e32 v42, v47, v47
	v_mul_f32_e32 v43, v49, v49
	v_fmac_f32_e32 v42, v46, v46
	v_fmac_f32_e32 v43, v48, v48
	v_add_f32_e32 v42, v42, v43
	v_mul_f32_e32 v43, v53, v53
	v_fmac_f32_e32 v43, v52, v52
	v_add_f32_e32 v42, v43, v42
	v_mul_f32_e32 v43, v51, v51
	v_fmac_f32_e32 v43, v50, v50
	v_add_f32_e32 v50, v43, v42
	s_waitcnt vmcnt(14)
	v_mov_b64_e32 v[42:43], v[200:201]
	v_mov_b64_e32 v[44:45], v[202:203]
	v_lshlrev_b32_e32 v46, 16, v42
	v_and_b32_e32 v47, 0xffff0000, v42
	v_lshlrev_b32_e32 v42, 16, v43
	v_and_b32_e32 v43, 0xffff0000, v43
	v_lshlrev_b32_e32 v48, 16, v44
	v_and_b32_e32 v49, 0xffff0000, v44
	v_lshlrev_b32_e32 v44, 16, v45
	v_and_b32_e32 v45, 0xffff0000, v45
	v_pk_add_f32 v[40:41], v[40:41], v[42:43]
	v_pk_add_f32 v[38:39], v[38:39], v[46:47]
	v_pk_add_f32 v[42:43], v[36:37], v[44:45]
	v_pk_add_f32 v[44:45], v[34:35], v[48:49]
	v_cvt_pk_bf16_f32 v34, v38, v39
	v_cvt_pk_bf16_f32 v35, v40, v41
	v_cvt_pk_bf16_f32 v36, v44, v45
	v_cvt_pk_bf16_f32 v37, v42, v43
	v_mov_b64_e32 v[224:225], v[34:35]
	v_mov_b64_e32 v[228:229], v[36:37]
	v_mov_b32_dpp v34, v248 row_shl:8 row_mask:0xf bank_mask:0x3
	v_mov_b32_dpp v35, v249 row_shl:8 row_mask:0xf bank_mask:0x3
	v_mov_b32_dpp v36, v250 row_shl:8 row_mask:0xf bank_mask:0x3
	v_mov_b32_dpp v37, v251 row_shl:8 row_mask:0xf bank_mask:0x3
	v_mov_b32_dpp v248, v224 row_shr:8 row_mask:0xf bank_mask:0xc
	v_mov_b32_dpp v249, v225 row_shr:8 row_mask:0xf bank_mask:0xc
	v_mov_b32_dpp v250, v228 row_shr:8 row_mask:0xf bank_mask:0xc
	v_mov_b32_dpp v251, v229 row_shr:8 row_mask:0xf bank_mask:0xc
	v_mad_i64_i32 v[224:225], s[98:99], v242, 1, v[54:55]
	v_mad_i64_i32 v[228:229], s[98:99], v243, 1, v[54:55]
	global_store_dwordx4 v[224:225], v[248:251], off
	global_store_dwordx4 v[228:229], v[34:37], off
	s_nop 1
	v_mul_f32_e32 v34, v39, v39
	v_mul_f32_e32 v35, v41, v41
	v_fmac_f32_e32 v34, v38, v38
	v_fmac_f32_e32 v35, v40, v40
	v_add_f32_e32 v34, v34, v35
	v_mul_f32_e32 v35, v45, v45
	v_fmac_f32_e32 v35, v44, v44
	v_add_f32_e32 v34, v35, v34
	v_mul_f32_e32 v35, v43, v43
	v_fmac_f32_e32 v35, v42, v42
	v_add_f32_e32 v34, v35, v34
	v_add_f32_e32 v34, v50, v34
	ds_bpermute_b32 v35, v145, v34
	s_waitcnt lgkmcnt(0)
	v_add_f32_e32 v34, v34, v35
	ds_bpermute_b32 v35, v144, v34
	s_and_saveexec_b64 s[58:59], s[38:39]
	s_cbranch_execz .LBB0_184
	s_waitcnt lgkmcnt(0)
	v_add_f32_e32 v36, v34, v35
	v_lshl_add_u64 v[34:35], s[56:57], 2, v[114:115]
	s_lshl_b32 s20, s76, 2
	v_lshl_add_u64 v[34:35], v[34:35], 0, s[20:21]
	v_add_co_u32_e32 v34, vcc, 0x2000, v34
	s_nop 1
	v_addc_co_u32_e32 v35, vcc, 0, v35, vcc
	global_store_dword v[34:35], v36, off offset:1024
; __device__ __forceinline__ unsigned cvt_pk_bf16(float lo, float hi) { f32x2 v = {lo, hi}; bf16x2_t_ b = __builtin_convertvector(v, bf16x2_t_); return __builtin_bit_cast(unsigned, b); }
; __device__ __forceinline__ float bf_lo(unsigned w) { return __uint_as_float(w << 16); }
; __device__ __forceinline__ float bf_hi(unsigned w) { return __uint_as_float(w & 0xffff0000u); }
;     __device__ __forceinline__ void operator()(f32x4 (&acc)[2][2][4][2], const Unit& u, int wr, int wc, int fr, int fq) const {
;         const int t0 = u.pm * 256 + wr * 64 + fr;
;         const int col0 = 256 * u.pn + 32 * wc + 8 * fq;
;         const float* bp0 = first ? ((t0 < NPROMPT) ? xp + (size_t)t0 * 1024 : xs + (size_t)(t0 - NPROMPT) * 1024) : out + (size_t)t0 * 1024;
; #pragma unroll
;         for (int ai = 0; ai < 2; ++ai)
; #pragma unroll
;             for (int m = 0; m < 4; ++m) {
;                 const int j = 128 * ai + 16 * m; float sq = 0.f;
; #pragma unroll
;                 for (int bj = 0; bj < 2; ++bj) {
;                     const size_t o = (size_t)j * 1024 + col0 + 128 * bj;
;                     f32x4 a, b;
;                     if (bb) { const u32x4 w = *(const u32x4*)(xb + (size_t)t0 * 1024 + o);
;                         a = (f32x4){bf_lo(w.x), bf_hi(w.x), bf_lo(w.y), bf_hi(w.y)}; b = (f32x4){bf_lo(w.z), bf_hi(w.z), bf_lo(w.w), bf_hi(w.w)}; }
;                     else { a = *(const f32x4*)(bp0 + o); b = *(const f32x4*)(bp0 + o + 4); }
;                     a = a + acc[ai][bj][m][0]; b = b + acc[ai][bj][m][1];
;                     if (wout) { float* op = out + (size_t)t0 * 1024 + o; *(f32x4*)op = a; *(f32x4*)(op + 4) = b; }
;                     u32x4 w; w.x = cvt_pk_bf16(a.x, a.y); w.y = cvt_pk_bf16(a.z, a.w); w.z = cvt_pk_bf16(b.x, b.y); w.w = cvt_pk_bf16(b.z, b.w);
;                     *(u32x4*)(xb + (size_t)t0 * 1024 + o) = w;
;                     sq += (a.x * a.x + a.y * a.y) + (a.z * a.z + a.w * a.w) + (b.x * b.x + b.y * b.y) + (b.z * b.z + b.w * b.w);
;                 }
;                 sq += __shfl_xor(sq, 16); sq += __shfl_xor(sq, 32);
;                 if (fq == 0) ss[(size_t)(t0 + j) * 16 + 4 * u.pn + wc] = sq;
.LBB0_184:
	s_or_b64 exec, exec, s[58:59]
	v_add_co_u32_e32 v38, vcc, 0x50000, v136
	s_nop 1
	v_addc_co_u32_e32 v39, vcc, 0, v137, vcc
	s_waitcnt lgkmcnt(0)
	s_waitcnt vmcnt(15)
	v_mov_b64_e32 v[34:35], v[204:205]
	v_mov_b64_e32 v[36:37], v[206:207]
	v_lshlrev_b32_e32 v40, 16, v34
	v_and_b32_e32 v41, 0xffff0000, v34
	v_lshlrev_b32_e32 v34, 16, v35
	v_and_b32_e32 v35, 0xffff0000, v35
	v_lshlrev_b32_e32 v42, 16, v36
	v_and_b32_e32 v43, 0xffff0000, v36
	v_lshlrev_b32_e32 v36, 16, v37
	v_and_b32_e32 v37, 0xffff0000, v37
	v_pk_add_f32 v[32:33], v[32:33], v[34:35]
	v_pk_add_f32 v[30:31], v[30:31], v[40:41]
	v_pk_add_f32 v[34:35], v[28:29], v[36:37]
	v_pk_add_f32 v[36:37], v[26:27], v[42:43]
	v_cvt_pk_bf16_f32 v26, v30, v31
	v_cvt_pk_bf16_f32 v27, v32, v33
	v_cvt_pk_bf16_f32 v28, v36, v37
	v_cvt_pk_bf16_f32 v29, v34, v35
	v_mov_b64_e32 v[248:249], v[26:27]
	v_mov_b64_e32 v[250:251], v[28:29]
	s_nop 1
	v_mul_f32_e32 v26, v31, v31
	v_mul_f32_e32 v27, v33, v33
	v_fmac_f32_e32 v26, v30, v30
	v_fmac_f32_e32 v27, v32, v32
	v_add_f32_e32 v26, v26, v27
	v_mul_f32_e32 v27, v37, v37
	v_fmac_f32_e32 v27, v36, v36
	v_add_f32_e32 v26, v27, v26
	v_mul_f32_e32 v27, v35, v35
	v_fmac_f32_e32 v27, v34, v34
	v_add_f32_e32 v34, v27, v26
	s_waitcnt vmcnt(14)
	v_mov_b64_e32 v[26:27], v[208:209]
	v_mov_b64_e32 v[28:29], v[210:211]
	v_lshlrev_b32_e32 v30, 16, v26
	v_and_b32_e32 v31, 0xffff0000, v26
	v_lshlrev_b32_e32 v26, 16, v27
	v_and_b32_e32 v27, 0xffff0000, v27
	v_lshlrev_b32_e32 v32, 16, v28
	v_and_b32_e32 v33, 0xffff0000, v28
	v_lshlrev_b32_e32 v28, 16, v29
	v_and_b32_e32 v29, 0xffff0000, v29
	v_pk_add_f32 v[24:25], v[24:25], v[26:27]
	v_pk_add_f32 v[22:23], v[22:23], v[30:31]
	v_pk_add_f32 v[26:27], v[20:21], v[28:29]
	v_pk_add_f32 v[28:29], v[18:19], v[32:33]
	v_cvt_pk_bf16_f32 v18, v22, v23
	v_cvt_pk_bf16_f32 v19, v24, v25
	v_cvt_pk_bf16_f32 v20, v28, v29
	v_cvt_pk_bf16_f32 v21, v26, v27
	v_mov_b64_e32 v[224:225], v[18:19]
	v_mov_b64_e32 v[228:229], v[20:21]
	v_mov_b32_dpp v18, v248 row_shl:8 row_mask:0xf bank_mask:0x3
	v_mov_b32_dpp v19, v249 row_shl:8 row_mask:0xf bank_mask:0x3
	v_mov_b32_dpp v20, v250 row_shl:8 row_mask:0xf bank_mask:0x3
	v_mov_b32_dpp v21, v251 row_shl:8 row_mask:0xf bank_mask:0x3
	v_mov_b32_dpp v248, v224 row_shr:8 row_mask:0xf bank_mask:0xc
	v_mov_b32_dpp v249, v225 row_shr:8 row_mask:0xf bank_mask:0xc
	v_mov_b32_dpp v250, v228 row_shr:8 row_mask:0xf bank_mask:0xc
	v_mov_b32_dpp v251, v229 row_shr:8 row_mask:0xf bank_mask:0xc
	v_mad_i64_i32 v[224:225], s[98:99], v242, 1, v[38:39]
	v_mad_i64_i32 v[228:229], s[98:99], v243, 1, v[38:39]
	global_store_dwordx4 v[224:225], v[248:251], off
	global_store_dwordx4 v[228:229], v[18:21], off
	s_nop 1
	v_mul_f32_e32 v18, v23, v23
	v_mul_f32_e32 v19, v25, v25
	v_fmac_f32_e32 v18, v22, v22
	v_fmac_f32_e32 v19, v24, v24
	v_add_f32_e32 v18, v18, v19
	v_mul_f32_e32 v19, v29, v29
	v_fmac_f32_e32 v19, v28, v28
	v_add_f32_e32 v18, v19, v18
	v_mul_f32_e32 v19, v27, v27
	v_fmac_f32_e32 v19, v26, v26
	v_add_f32_e32 v18, v19, v18
	v_add_f32_e32 v18, v34, v18
	ds_bpermute_b32 v19, v145, v18
	s_waitcnt lgkmcnt(0)
	v_add_f32_e32 v18, v18, v19
	ds_bpermute_b32 v19, v144, v18
	s_and_saveexec_b64 s[58:59], s[38:39]
	s_cbranch_execz .LBB0_186
	s_waitcnt lgkmcnt(0)
	v_add_f32_e32 v20, v18, v19
	v_lshl_add_u64 v[18:19], s[56:57], 2, v[114:115]
	s_lshl_b32 s20, s76, 2
	v_lshl_add_u64 v[18:19], v[18:19], 0, s[20:21]
	v_add_co_u32_e32 v18, vcc, 0x2000, v18
	s_nop 1
	v_addc_co_u32_e32 v19, vcc, 0, v19, vcc
	global_store_dword v[18:19], v20, off offset:2048
.LBB0_186:
	s_or_b64 exec, exec, s[58:59]
	v_add_co_u32_e32 v22, vcc, 0x58000, v136
	s_nop 1
	v_addc_co_u32_e32 v23, vcc, 0, v137, vcc
	s_waitcnt lgkmcnt(0)
	s_waitcnt vmcnt(15)
	v_mov_b64_e32 v[18:19], v[212:213]
	v_mov_b64_e32 v[20:21], v[214:215]
	v_lshlrev_b32_e32 v24, 16, v18
	v_and_b32_e32 v25, 0xffff0000, v18
	v_lshlrev_b32_e32 v18, 16, v19
	v_and_b32_e32 v19, 0xffff0000, v19
	v_lshlrev_b32_e32 v26, 16, v20
	v_and_b32_e32 v27, 0xffff0000, v20
	v_lshlrev_b32_e32 v20, 16, v21
	v_and_b32_e32 v21, 0xffff0000, v21
	v_pk_add_f32 v[16:17], v[16:17], v[18:19]
	v_pk_add_f32 v[14:15], v[14:15], v[24:25]
	v_pk_add_f32 v[18:19], v[12:13], v[20:21]
	v_pk_add_f32 v[20:21], v[10:11], v[26:27]
	v_cvt_pk_bf16_f32 v10, v14, v15
	v_cvt_pk_bf16_f32 v11, v16, v17
	v_cvt_pk_bf16_f32 v12, v20, v21
	v_cvt_pk_bf16_f32 v13, v18, v19
	v_mov_b64_e32 v[248:249], v[10:11]
	v_mov_b64_e32 v[250:251], v[12:13]
	s_nop 1
	v_mul_f32_e32 v10, v15, v15
	v_mul_f32_e32 v11, v17, v17
	v_fmac_f32_e32 v10, v14, v14
	v_fmac_f32_e32 v11, v16, v16
	v_add_f32_e32 v10, v10, v11
	v_mul_f32_e32 v11, v21, v21
	v_fmac_f32_e32 v11, v20, v20
	v_add_f32_e32 v10, v11, v10
	v_mul_f32_e32 v11, v19, v19
	v_fmac_f32_e32 v11, v18, v18
	v_add_f32_e32 v18, v11, v10
	s_waitcnt vmcnt(14)
	v_mov_b64_e32 v[10:11], v[236:237]
	v_mov_b64_e32 v[12:13], v[238:239]
	v_lshlrev_b32_e32 v14, 16, v10
	v_and_b32_e32 v15, 0xffff0000, v10
	v_lshlrev_b32_e32 v10, 16, v11
	v_and_b32_e32 v11, 0xffff0000, v11
	v_lshlrev_b32_e32 v16, 16, v12
	v_and_b32_e32 v17, 0xffff0000, v12
	v_lshlrev_b32_e32 v12, 16, v13
	v_and_b32_e32 v13, 0xffff0000, v13
	v_pk_add_f32 v[8:9], v[8:9], v[10:11]
	v_pk_add_f32 v[6:7], v[6:7], v[14:15]
	v_pk_add_f32 v[10:11], v[4:5], v[12:13]
	v_pk_add_f32 v[12:13], v[2:3], v[16:17]
	v_cvt_pk_bf16_f32 v2, v6, v7
	v_cvt_pk_bf16_f32 v3, v8, v9
	v_cvt_pk_bf16_f32 v4, v12, v13
	v_cvt_pk_bf16_f32 v5, v10, v11
	v_mov_b64_e32 v[224:225], v[2:3]
	v_mov_b64_e32 v[228:229], v[4:5]
	v_mov_b32_dpp v2, v248 row_shl:8 row_mask:0xf bank_mask:0x3
	v_mov_b32_dpp v3, v249 row_shl:8 row_mask:0xf bank_mask:0x3
	v_mov_b32_dpp v4, v250 row_shl:8 row_mask:0xf bank_mask:0x3
	v_mov_b32_dpp v5, v251 row_shl:8 row_mask:0xf bank_mask:0x3
	v_mov_b32_dpp v248, v224 row_shr:8 row_mask:0xf bank_mask:0xc
	v_mov_b32_dpp v249, v225 row_shr:8 row_mask:0xf bank_mask:0xc
	v_mov_b32_dpp v250, v228 row_shr:8 row_mask:0xf bank_mask:0xc
	v_mov_b32_dpp v251, v229 row_shr:8 row_mask:0xf bank_mask:0xc
	v_mad_i64_i32 v[224:225], s[98:99], v242, 1, v[22:23]
	v_mad_i64_i32 v[228:229], s[98:99], v243, 1, v[22:23]
	global_store_dwordx4 v[224:225], v[248:251], off
	global_store_dwordx4 v[228:229], v[2:5], off
	s_nop 1
	v_mul_f32_e32 v2, v7, v7
	v_mul_f32_e32 v3, v9, v9
	v_fmac_f32_e32 v2, v6, v6
	v_fmac_f32_e32 v3, v8, v8
	v_add_f32_e32 v2, v2, v3
	v_mul_f32_e32 v3, v13, v13
	v_fmac_f32_e32 v3, v12, v12
	v_add_f32_e32 v2, v3, v2
	v_mul_f32_e32 v3, v11, v11
	v_fmac_f32_e32 v3, v10, v10
	v_add_f32_e32 v2, v3, v2
	v_add_f32_e32 v2, v18, v2
	ds_bpermute_b32 v3, v145, v2
	s_waitcnt lgkmcnt(0)
	v_add_f32_e32 v2, v2, v3
	ds_bpermute_b32 v3, v144, v2
	s_and_saveexec_b64 s[58:59], s[38:39]
	s_cbranch_execz .LBB0_188
	s_waitcnt lgkmcnt(0)
	v_add_f32_e32 v4, v2, v3
	v_lshl_add_u64 v[2:3], s[56:57], 2, v[114:115]
	s_lshl_b32 s20, s76, 2
	v_lshl_add_u64 v[2:3], v[2:3], 0, s[20:21]
	v_add_co_u32_e32 v2, vcc, 0x2000, v2
	s_nop 1
	v_addc_co_u32_e32 v3, vcc, 0, v3, vcc
	global_store_dword v[2:3], v4, off offset:3072

; __device__ __forceinline__ unsigned cvt_pk_bf16(float lo, float hi) { f32x2 v = {lo, hi}; bf16x2_t_ b = __builtin_convertvector(v, bf16x2_t_); return __builtin_bit_cast(unsigned, b); }
; __device__ __forceinline__ float bf_lo(unsigned w) { return __uint_as_float(w << 16); }
; __device__ __forceinline__ float bf_hi(unsigned w) { return __uint_as_float(w & 0xffff0000u); }
;     __device__ __forceinline__ void operator()(f32x4 (&acc)[2][2][4][2], const Unit& u, int wr, int wc, int fr, int fq) const {
;         const int t0 = u.pm * 256 + wr * 64 + fr;
;         const int col0 = 256 * u.pn + 32 * wc + 8 * fq;
;         const float* bp0 = first ? ((t0 < NPROMPT) ? xp + (size_t)t0 * 1024 : xs + (size_t)(t0 - NPROMPT) * 1024) : out + (size_t)t0 * 1024;
; #pragma unroll
;         for (int ai = 0; ai < 2; ++ai)
; #pragma unroll
;             for (int m = 0; m < 4; ++m) {
;                 const int j = 128 * ai + 16 * m; float sq = 0.f;
; #pragma unroll
;                 for (int bj = 0; bj < 2; ++bj) {
;                     const size_t o = (size_t)j * 1024 + col0 + 128 * bj;
;                     f32x4 a, b;
;                     if (bb) { const u32x4 w = *(const u32x4*)(xb + (size_t)t0 * 1024 + o);
;                         a = (f32x4){bf_lo(w.x), bf_hi(w.x), bf_lo(w.y), bf_hi(w.y)}; b = (f32x4){bf_lo(w.z), bf_hi(w.z), bf_lo(w.w), bf_hi(w.w)}; }
;                     else { a = *(const f32x4*)(bp0 + o); b = *(const f32x4*)(bp0 + o + 4); }
;                     a = a + acc[ai][bj][m][0]; b = b + acc[ai][bj][m][1];
;                     if (wout) { float* op = out + (size_t)t0 * 1024 + o; *(f32x4*)op = a; *(f32x4*)(op + 4) = b; }
;                     u32x4 w; w.x = cvt_pk_bf16(a.x, a.y); w.y = cvt_pk_bf16(a.z, a.w); w.z = cvt_pk_bf16(b.x, b.y); w.w = cvt_pk_bf16(b.z, b.w);
;                     *(u32x4*)(xb + (size_t)t0 * 1024 + o) = w;
;                     sq += (a.x * a.x + a.y * a.y) + (a.z * a.z + a.w * a.w) + (b.x * b.x + b.y * b.y) + (b.z * b.z + b.w * b.w);
;                 }
;                 sq += __shfl_xor(sq, 16); sq += __shfl_xor(sq, 32);
;                 if (fq == 0) ss[(size_t)(t0 + j) * 16 + 4 * u.pn + wc] = sq;
.LBB0_348:
	v_lshl_add_u32 v138, s54, 8, v140
	v_and_b32_e32 v145, 64, v219
	v_ashrrev_i32_e32 v139, 31, v138
	v_xor_b32_e32 v144, 16, v219
	v_add_u32_e32 v148, 64, v145
	v_lshl_or_b32 v136, s20, 8, v142
	v_lshlrev_b64 v[146:147], 11, v[138:139]
	v_cmp_lt_i32_e32 vcc, v144, v148
	v_ashrrev_i32_e32 v137, 31, v136
	v_lshl_add_u64 v[146:147], s[24:25], 0, v[146:147]
	v_cndmask_b32_e32 v144, v219, v144, vcc
	v_lshlrev_b32_e32 v145, 2, v144
	v_xor_b32_e32 v144, 32, v219
	v_lshl_add_u64 v[136:137], v[136:137], 1, v[146:147]
	v_cmp_lt_i32_e32 vcc, v144, v148
	global_load_dwordx4 v[146:149], v[136:137], off
	s_mov_b32 s101, 0
	global_load_dwordx4 v[154:157], v[136:137], off offset:64
	s_mov_b32 s100, 0x8000
	v_lshl_add_u64 v[240:241], v[136:137], 0, s[100:101]
	global_load_dwordx4 v[158:161], v[240:241], off
	global_load_dwordx4 v[162:165], v[240:241], off offset:64
	s_mov_b32 s100, 0x10000
	v_lshl_add_u64 v[240:241], v[136:137], 0, s[100:101]
	global_load_dwordx4 v[166:169], v[240:241], off
	global_load_dwordx4 v[170:173], v[240:241], off offset:64
	s_mov_b32 s100, 0x18000
	v_lshl_add_u64 v[240:241], v[136:137], 0, s[100:101]
	global_load_dwordx4 v[174:177], v[240:241], off
	global_load_dwordx4 v[178:181], v[240:241], off offset:64
	s_mov_b32 s100, 0x40000
	v_lshl_add_u64 v[240:241], v[136:137], 0, s[100:101]
	global_load_dwordx4 v[182:185], v[240:241], off
	global_load_dwordx4 v[186:189], v[240:241], off offset:64
	s_mov_b32 s100, 0x48000
	v_lshl_add_u64 v[240:241], v[136:137], 0, s[100:101]
	global_load_dwordx4 v[196:199], v[240:241], off
	global_load_dwordx4 v[200:203], v[240:241], off offset:64
	s_mov_b32 s100, 0x50000
	v_lshl_add_u64 v[240:241], v[136:137], 0, s[100:101]
	global_load_dwordx4 v[204:207], v[240:241], off
	global_load_dwordx4 v[208:211], v[240:241], off offset:64
	s_mov_b32 s100, 0x58000
	v_lshl_add_u64 v[240:241], v[136:137], 0, s[100:101]
	global_load_dwordx4 v[212:215], v[240:241], off
	global_load_dwordx4 v[236:239], v[240:241], off offset:64
	v_and_b32_e32 v242, 8, v219
	v_mul_i32_i24_e32 v242, 0xfffff808, v242
	v_add_u32_e32 v243, 0x4000, v242
	v_readlane_b32 s80, v254, 33
	v_cndmask_b32_e32 v144, v219, v144, vcc
	v_lshlrev_b32_e32 v144, 2, v144
	s_lshl_b32 s54, s20, 2
	v_readlane_b32 s81, v254, 34
	s_ashr_i32 s55, s54, 31
	s_waitcnt vmcnt(15)
	v_lshlrev_b32_e32 v150, 16, v146
	v_and_b32_e32 v151, 0xffff0000, v146
	v_lshlrev_b32_e32 v146, 16, v147
	v_and_b32_e32 v147, 0xffff0000, v147
	v_lshlrev_b32_e32 v152, 16, v148
	v_and_b32_e32 v153, 0xffff0000, v148
	v_lshlrev_b32_e32 v148, 16, v149
	v_and_b32_e32 v149, 0xffff0000, v149
	v_pk_add_f32 v[128:129], v[128:129], v[146:147]
	v_pk_add_f32 v[126:127], v[126:127], v[150:151]
	v_pk_add_f32 v[146:147], v[124:125], v[148:149]
	v_pk_add_f32 v[148:149], v[122:123], v[152:153]
	v_cvt_pk_bf16_f32 v122, v126, v127
	v_cvt_pk_bf16_f32 v123, v128, v129
	v_cvt_pk_bf16_f32 v124, v148, v149
	v_cvt_pk_bf16_f32 v125, v146, v147
	v_mov_b64_e32 v[248:249], v[122:123]
	v_mov_b64_e32 v[250:251], v[124:125]
	s_nop 1
	v_mul_f32_e32 v122, v127, v127
	v_mul_f32_e32 v123, v129, v129
	v_fmac_f32_e32 v122, v126, v126
	v_fmac_f32_e32 v123, v128, v128
	v_add_f32_e32 v122, v122, v123
	v_mul_f32_e32 v123, v149, v149
	v_fmac_f32_e32 v123, v148, v148
	v_add_f32_e32 v122, v123, v122
	v_mul_f32_e32 v123, v147, v147
	v_fmac_f32_e32 v123, v146, v146
	v_add_f32_e32 v146, v123, v122
	s_waitcnt vmcnt(14)
	v_mov_b64_e32 v[122:123], v[154:155]
	v_mov_b64_e32 v[124:125], v[156:157]
	v_lshlrev_b32_e32 v126, 16, v122
	v_and_b32_e32 v127, 0xffff0000, v122
	v_lshlrev_b32_e32 v122, 16, v123
	v_and_b32_e32 v123, 0xffff0000, v123
	v_lshlrev_b32_e32 v128, 16, v124
	v_and_b32_e32 v129, 0xffff0000, v124
	v_lshlrev_b32_e32 v124, 16, v125
	v_and_b32_e32 v125, 0xffff0000, v125
	v_pk_add_f32 v[120:121], v[120:121], v[122:123]
	v_pk_add_f32 v[118:119], v[118:119], v[126:127]
	v_pk_add_f32 v[122:123], v[116:117], v[124:125]
	v_pk_add_f32 v[124:125], v[114:115], v[128:129]
	v_cvt_pk_bf16_f32 v114, v118, v119
	v_cvt_pk_bf16_f32 v115, v120, v121
	v_cvt_pk_bf16_f32 v116, v124, v125
	v_cvt_pk_bf16_f32 v117, v122, v123
	v_mov_b64_e32 v[224:225], v[114:115]
	v_mov_b64_e32 v[228:229], v[116:117]
	v_mov_b32_dpp v114, v248 row_shl:8 row_mask:0xf bank_mask:0x3
	v_mov_b32_dpp v115, v249 row_shl:8 row_mask:0xf bank_mask:0x3
	v_mov_b32_dpp v116, v250 row_shl:8 row_mask:0xf bank_mask:0x3
	v_mov_b32_dpp v117, v251 row_shl:8 row_mask:0xf bank_mask:0x3
	v_mov_b32_dpp v248, v224 row_shr:8 row_mask:0xf bank_mask:0xc
	v_mov_b32_dpp v249, v225 row_shr:8 row_mask:0xf bank_mask:0xc
	v_mov_b32_dpp v250, v228 row_shr:8 row_mask:0xf bank_mask:0xc
	v_mov_b32_dpp v251, v229 row_shr:8 row_mask:0xf bank_mask:0xc
	v_mad_i64_i32 v[224:225], s[98:99], v242, 1, v[136:137]
	v_mad_i64_i32 v[228:229], s[98:99], v243, 1, v[136:137]
	global_store_dwordx4 v[224:225], v[248:251], off
	global_store_dwordx4 v[228:229], v[114:117], off
	s_nop 1
	v_mul_f32_e32 v114, v119, v119
	v_mul_f32_e32 v115, v121, v121
	v_fmac_f32_e32 v114, v118, v118
	v_fmac_f32_e32 v115, v120, v120
	v_add_f32_e32 v114, v114, v115
	v_mul_f32_e32 v115, v125, v125
	v_fmac_f32_e32 v115, v124, v124
	v_add_f32_e32 v114, v115, v114
	v_mul_f32_e32 v115, v123, v123
	v_fmac_f32_e32 v115, v122, v122
	v_add_f32_e32 v114, v115, v114
	v_add_f32_e32 v114, v146, v114
	ds_bpermute_b32 v115, v145, v114
	s_waitcnt lgkmcnt(0)
	v_add_f32_e32 v116, v114, v115
	ds_bpermute_b32 v117, v144, v116
	v_lshlrev_b64 v[114:115], 6, v[138:139]
	v_lshl_add_u64 v[114:115], s[80:81], 0, v[114:115]
	s_and_saveexec_b64 s[56:57], s[38:39]
	s_cbranch_execz .LBB0_350
	v_lshl_add_u64 v[118:119], s[54:55], 2, v[114:115]
	s_lshl_b32 s20, s74, 2
	v_lshl_add_u64 v[118:119], v[118:119], 0, s[20:21]
	s_waitcnt lgkmcnt(0)
	v_add_f32_e32 v116, v116, v117
	global_store_dword v[118:119], v116, off
; __device__ __forceinline__ unsigned cvt_pk_bf16(float lo, float hi) { f32x2 v = {lo, hi}; bf16x2_t_ b = __builtin_convertvector(v, bf16x2_t_); return __builtin_bit_cast(unsigned, b); }
; __device__ __forceinline__ float bf_lo(unsigned w) { return __uint_as_float(w << 16); }
; __device__ __forceinline__ float bf_hi(unsigned w) { return __uint_as_float(w & 0xffff0000u); }
;     __device__ __forceinline__ void operator()(f32x4 (&acc)[2][2][4][2], const Unit& u, int wr, int wc, int fr, int fq) const {
;         const int t0 = u.pm * 256 + wr * 64 + fr;
;         const int col0 = 256 * u.pn + 32 * wc + 8 * fq;
;         const float* bp0 = first ? ((t0 < NPROMPT) ? xp + (size_t)t0 * 1024 : xs + (size_t)(t0 - NPROMPT) * 1024) : out + (size_t)t0 * 1024;
; #pragma unroll
;         for (int ai = 0; ai < 2; ++ai)
; #pragma unroll
;             for (int m = 0; m < 4; ++m) {
;                 const int j = 128 * ai + 16 * m; float sq = 0.f;
; #pragma unroll
;                 for (int bj = 0; bj < 2; ++bj) {
;                     const size_t o = (size_t)j * 1024 + col0 + 128 * bj;
;                     f32x4 a, b;
;                     if (bb) { const u32x4 w = *(const u32x4*)(xb + (size_t)t0 * 1024 + o);
;                         a = (f32x4){bf_lo(w.x), bf_hi(w.x), bf_lo(w.y), bf_hi(w.y)}; b = (f32x4){bf_lo(w.z), bf_hi(w.z), bf_lo(w.w), bf_hi(w.w)}; }
;                     else { a = *(const f32x4*)(bp0 + o); b = *(const f32x4*)(bp0 + o + 4); }
;                     a = a + acc[ai][bj][m][0]; b = b + acc[ai][bj][m][1];
;                     if (wout) { float* op = out + (size_t)t0 * 1024 + o; *(f32x4*)op = a; *(f32x4*)(op + 4) = b; }
;                     u32x4 w; w.x = cvt_pk_bf16(a.x, a.y); w.y = cvt_pk_bf16(a.z, a.w); w.z = cvt_pk_bf16(b.x, b.y); w.w = cvt_pk_bf16(b.z, b.w);
;                     *(u32x4*)(xb + (size_t)t0 * 1024 + o) = w;
;                     sq += (a.x * a.x + a.y * a.y) + (a.z * a.z + a.w * a.w) + (b.x * b.x + b.y * b.y) + (b.z * b.z + b.w * b.w);
;                 }
;                 sq += __shfl_xor(sq, 16); sq += __shfl_xor(sq, 32);
;                 if (fq == 0) ss[(size_t)(t0 + j) * 16 + 4 * u.pn + wc] = sq;
.LBB0_350:
	s_or_b64 exec, exec, s[56:57]
	v_add_co_u32_e32 v120, vcc, 0x8000, v136
	s_nop 1
	v_addc_co_u32_e32 v121, vcc, 0, v137, vcc
	s_waitcnt lgkmcnt(0)
	s_waitcnt vmcnt(15)
	v_mov_b64_e32 v[116:117], v[158:159]
	v_mov_b64_e32 v[118:119], v[160:161]
	v_lshlrev_b32_e32 v122, 16, v116
	v_and_b32_e32 v123, 0xffff0000, v116
	v_lshlrev_b32_e32 v116, 16, v117
	v_and_b32_e32 v117, 0xffff0000, v117
	v_lshlrev_b32_e32 v124, 16, v118
	v_and_b32_e32 v125, 0xffff0000, v118
	v_lshlrev_b32_e32 v118, 16, v119
	v_and_b32_e32 v119, 0xffff0000, v119
	v_pk_add_f32 v[112:113], v[112:113], v[116:117]
	v_pk_add_f32 v[110:111], v[110:111], v[122:123]
	v_pk_add_f32 v[116:117], v[108:109], v[118:119]
	v_pk_add_f32 v[118:119], v[106:107], v[124:125]
	v_cvt_pk_bf16_f32 v106, v110, v111
	v_cvt_pk_bf16_f32 v107, v112, v113
	v_cvt_pk_bf16_f32 v108, v118, v119
	v_cvt_pk_bf16_f32 v109, v116, v117
	v_mov_b64_e32 v[248:249], v[106:107]
	v_mov_b64_e32 v[250:251], v[108:109]
	s_nop 1
	v_mul_f32_e32 v106, v111, v111
	v_mul_f32_e32 v107, v113, v113
	v_fmac_f32_e32 v106, v110, v110
	v_fmac_f32_e32 v107, v112, v112
	v_add_f32_e32 v106, v106, v107
	v_mul_f32_e32 v107, v119, v119
	v_fmac_f32_e32 v107, v118, v118
	v_add_f32_e32 v106, v107, v106
	v_mul_f32_e32 v107, v117, v117
	v_fmac_f32_e32 v107, v116, v116
	v_add_f32_e32 v116, v107, v106
	s_waitcnt vmcnt(14)
	v_mov_b64_e32 v[106:107], v[162:163]
	v_mov_b64_e32 v[108:109], v[164:165]
	v_lshlrev_b32_e32 v110, 16, v106
	v_and_b32_e32 v111, 0xffff0000, v106
	v_lshlrev_b32_e32 v106, 16, v107
	v_and_b32_e32 v107, 0xffff0000, v107
	v_lshlrev_b32_e32 v112, 16, v108
	v_and_b32_e32 v113, 0xffff0000, v108
	v_lshlrev_b32_e32 v108, 16, v109
	v_and_b32_e32 v109, 0xffff0000, v109
	v_pk_add_f32 v[104:105], v[104:105], v[106:107]
	v_pk_add_f32 v[102:103], v[102:103], v[110:111]
	v_pk_add_f32 v[106:107], v[100:101], v[108:109]
	v_pk_add_f32 v[108:109], v[98:99], v[112:113]
	v_cvt_pk_bf16_f32 v98, v102, v103
	v_cvt_pk_bf16_f32 v99, v104, v105
	v_cvt_pk_bf16_f32 v100, v108, v109
	v_cvt_pk_bf16_f32 v101, v106, v107
	v_mov_b64_e32 v[224:225], v[98:99]
	v_mov_b64_e32 v[228:229], v[100:101]
	v_mov_b32_dpp v98, v248 row_shl:8 row_mask:0xf bank_mask:0x3
	v_mov_b32_dpp v99, v249 row_shl:8 row_mask:0xf bank_mask:0x3
	v_mov_b32_dpp v100, v250 row_shl:8 row_mask:0xf bank_mask:0x3
	v_mov_b32_dpp v101, v251 row_shl:8 row_mask:0xf bank_mask:0x3
	v_mov_b32_dpp v248, v224 row_shr:8 row_mask:0xf bank_mask:0xc
	v_mov_b32_dpp v249, v225 row_shr:8 row_mask:0xf bank_mask:0xc
	v_mov_b32_dpp v250, v228 row_shr:8 row_mask:0xf bank_mask:0xc
	v_mov_b32_dpp v251, v229 row_shr:8 row_mask:0xf bank_mask:0xc
	v_mad_i64_i32 v[224:225], s[98:99], v242, 1, v[120:121]
	v_mad_i64_i32 v[228:229], s[98:99], v243, 1, v[120:121]
	global_store_dwordx4 v[224:225], v[248:251], off
	global_store_dwordx4 v[228:229], v[98:101], off
	s_nop 1
	v_mul_f32_e32 v98, v103, v103
	v_mul_f32_e32 v99, v105, v105
	v_fmac_f32_e32 v98, v102, v102
	v_fmac_f32_e32 v99, v104, v104
	v_add_f32_e32 v98, v98, v99
	v_mul_f32_e32 v99, v109, v109
	v_fmac_f32_e32 v99, v108, v108
	v_add_f32_e32 v98, v99, v98
	v_mul_f32_e32 v99, v107, v107
	v_fmac_f32_e32 v99, v106, v106
	v_add_f32_e32 v98, v99, v98
	v_add_f32_e32 v98, v116, v98
	ds_bpermute_b32 v99, v145, v98
	s_waitcnt lgkmcnt(0)
	v_add_f32_e32 v98, v98, v99
	ds_bpermute_b32 v99, v144, v98
	s_and_saveexec_b64 s[56:57], s[38:39]
	s_cbranch_execz .LBB0_352
	s_waitcnt lgkmcnt(0)
	v_add_f32_e32 v100, v98, v99
	v_or_b32_e32 v98, 16, v138
	v_ashrrev_i32_e32 v99, 31, v98
	v_lshlrev_b64 v[98:99], 6, v[98:99]
	v_lshl_add_u64 v[98:99], s[80:81], 0, v[98:99]
	v_lshl_add_u64 v[98:99], s[54:55], 2, v[98:99]
	s_lshl_b32 s20, s74, 2
	v_lshl_add_u64 v[98:99], v[98:99], 0, s[20:21]
	global_store_dword v[98:99], v100, off
.LBB0_352:
	s_or_b64 exec, exec, s[56:57]
	v_add_co_u32_e32 v102, vcc, 0x10000, v136
	s_nop 1
	v_addc_co_u32_e32 v103, vcc, 0, v137, vcc
	s_waitcnt lgkmcnt(0)
	s_waitcnt vmcnt(15)
	v_mov_b64_e32 v[98:99], v[166:167]
	v_mov_b64_e32 v[100:101], v[168:169]
	v_lshlrev_b32_e32 v104, 16, v98
	v_and_b32_e32 v105, 0xffff0000, v98
	v_lshlrev_b32_e32 v98, 16, v99
	v_and_b32_e32 v99, 0xffff0000, v99
	v_lshlrev_b32_e32 v106, 16, v100
	v_and_b32_e32 v107, 0xffff0000, v100
	v_lshlrev_b32_e32 v100, 16, v101
	v_and_b32_e32 v101, 0xffff0000, v101
	v_pk_add_f32 v[96:97], v[96:97], v[98:99]
	v_pk_add_f32 v[94:95], v[94:95], v[104:105]
	v_pk_add_f32 v[98:99], v[92:93], v[100:101]
	v_pk_add_f32 v[100:101], v[90:91], v[106:107]
	v_cvt_pk_bf16_f32 v90, v94, v95
	v_cvt_pk_bf16_f32 v91, v96, v97
	v_cvt_pk_bf16_f32 v92, v100, v101
	v_cvt_pk_bf16_f32 v93, v98, v99
	v_mov_b64_e32 v[248:249], v[90:91]
	v_mov_b64_e32 v[250:251], v[92:93]
	s_nop 1
	v_mul_f32_e32 v90, v95, v95
	v_mul_f32_e32 v91, v97, v97
	v_fmac_f32_e32 v90, v94, v94
	v_fmac_f32_e32 v91, v96, v96
	v_add_f32_e32 v90, v90, v91
	v_mul_f32_e32 v91, v101, v101
	v_fmac_f32_e32 v91, v100, v100
	v_add_f32_e32 v90, v91, v90
	v_mul_f32_e32 v91, v99, v99
	v_fmac_f32_e32 v91, v98, v98
	v_add_f32_e32 v98, v91, v90
	s_waitcnt vmcnt(14)
	v_mov_b64_e32 v[90:91], v[170:171]
	v_mov_b64_e32 v[92:93], v[172:173]
	v_lshlrev_b32_e32 v94, 16, v90
	v_and_b32_e32 v95, 0xffff0000, v90
	v_lshlrev_b32_e32 v90, 16, v91
	v_and_b32_e32 v91, 0xffff0000, v91
	v_lshlrev_b32_e32 v96, 16, v92
	v_and_b32_e32 v97, 0xffff0000, v92
	v_lshlrev_b32_e32 v92, 16, v93
	v_and_b32_e32 v93, 0xffff0000, v93
	v_pk_add_f32 v[88:89], v[88:89], v[90:91]
	v_pk_add_f32 v[86:87], v[86:87], v[94:95]
	v_pk_add_f32 v[90:91], v[84:85], v[92:93]
	v_pk_add_f32 v[92:93], v[82:83], v[96:97]
	v_cvt_pk_bf16_f32 v82, v86, v87
	v_cvt_pk_bf16_f32 v83, v88, v89
	v_cvt_pk_bf16_f32 v84, v92, v93
	v_cvt_pk_bf16_f32 v85, v90, v91
	v_mov_b64_e32 v[224:225], v[82:83]
	v_mov_b64_e32 v[228:229], v[84:85]
	v_mov_b32_dpp v82, v248 row_shl:8 row_mask:0xf bank_mask:0x3
	v_mov_b32_dpp v83, v249 row_shl:8 row_mask:0xf bank_mask:0x3
	v_mov_b32_dpp v84, v250 row_shl:8 row_mask:0xf bank_mask:0x3
	v_mov_b32_dpp v85, v251 row_shl:8 row_mask:0xf bank_mask:0x3
	v_mov_b32_dpp v248, v224 row_shr:8 row_mask:0xf bank_mask:0xc
	v_mov_b32_dpp v249, v225 row_shr:8 row_mask:0xf bank_mask:0xc
	v_mov_b32_dpp v250, v228 row_shr:8 row_mask:0xf bank_mask:0xc
	v_mov_b32_dpp v251, v229 row_shr:8 row_mask:0xf bank_mask:0xc
	v_mad_i64_i32 v[224:225], s[98:99], v242, 1, v[102:103]
	v_mad_i64_i32 v[228:229], s[98:99], v243, 1, v[102:103]
	global_store_dwordx4 v[224:225], v[248:251], off
	global_store_dwordx4 v[228:229], v[82:85], off
	s_nop 1
	v_mul_f32_e32 v82, v87, v87
	v_mul_f32_e32 v83, v89, v89
	v_fmac_f32_e32 v82, v86, v86
	v_fmac_f32_e32 v83, v88, v88
	v_add_f32_e32 v82, v82, v83
	v_mul_f32_e32 v83, v93, v93
	v_fmac_f32_e32 v83, v92, v92
	v_add_f32_e32 v82, v83, v82
	v_mul_f32_e32 v83, v91, v91
	v_fmac_f32_e32 v83, v90, v90
	v_add_f32_e32 v82, v83, v82
	v_add_f32_e32 v82, v98, v82
	ds_bpermute_b32 v83, v145, v82
	s_waitcnt lgkmcnt(0)
	v_add_f32_e32 v82, v82, v83
	ds_bpermute_b32 v83, v144, v82
	s_and_saveexec_b64 s[56:57], s[38:39]
	s_cbranch_execz .LBB0_354
; __device__ __forceinline__ unsigned cvt_pk_bf16(float lo, float hi) { f32x2 v = {lo, hi}; bf16x2_t_ b = __builtin_convertvector(v, bf16x2_t_); return __builtin_bit_cast(unsigned, b); }
; __device__ __forceinline__ float bf_lo(unsigned w) { return __uint_as_float(w << 16); }
; __device__ __forceinline__ float bf_hi(unsigned w) { return __uint_as_float(w & 0xffff0000u); }
;     __device__ __forceinline__ void operator()(f32x4 (&acc)[2][2][4][2], const Unit& u, int wr, int wc, int fr, int fq) const {
;         const int t0 = u.pm * 256 + wr * 64 + fr;
;         const int col0 = 256 * u.pn + 32 * wc + 8 * fq;
;         const float* bp0 = first ? ((t0 < NPROMPT) ? xp + (size_t)t0 * 1024 : xs + (size_t)(t0 - NPROMPT) * 1024) : out + (size_t)t0 * 1024;
; #pragma unroll
;         for (int ai = 0; ai < 2; ++ai)
; #pragma unroll
;             for (int m = 0; m < 4; ++m) {
;                 const int j = 128 * ai + 16 * m; float sq = 0.f;
; #pragma unroll
;                 for (int bj = 0; bj < 2; ++bj) {
;                     const size_t o = (size_t)j * 1024 + col0 + 128 * bj;
;                     f32x4 a, b;
;                     if (bb) { const u32x4 w = *(const u32x4*)(xb + (size_t)t0 * 1024 + o);
;                         a = (f32x4){bf_lo(w.x), bf_hi(w.x), bf_lo(w.y), bf_hi(w.y)}; b = (f32x4){bf_lo(w.z), bf_hi(w.z), bf_lo(w.w), bf_hi(w.w)}; }
;                     else { a = *(const f32x4*)(bp0 + o); b = *(const f32x4*)(bp0 + o + 4); }
;                     a = a + acc[ai][bj][m][0]; b = b + acc[ai][bj][m][1];
;                     if (wout) { float* op = out + (size_t)t0 * 1024 + o; *(f32x4*)op = a; *(f32x4*)(op + 4) = b; }
;                     u32x4 w; w.x = cvt_pk_bf16(a.x, a.y); w.y = cvt_pk_bf16(a.z, a.w); w.z = cvt_pk_bf16(b.x, b.y); w.w = cvt_pk_bf16(b.z, b.w);
;                     *(u32x4*)(xb + (size_t)t0 * 1024 + o) = w;
;                     sq += (a.x * a.x + a.y * a.y) + (a.z * a.z + a.w * a.w) + (b.x * b.x + b.y * b.y) + (b.z * b.z + b.w * b.w);
;                 }
;                 sq += __shfl_xor(sq, 16); sq += __shfl_xor(sq, 32);
;                 if (fq == 0) ss[(size_t)(t0 + j) * 16 + 4 * u.pn + wc] = sq;
	s_waitcnt lgkmcnt(0)
	v_add_f32_e32 v84, v82, v83
	v_or_b32_e32 v82, 32, v138
	v_ashrrev_i32_e32 v83, 31, v82
	v_lshlrev_b64 v[82:83], 6, v[82:83]
	v_lshl_add_u64 v[82:83], s[80:81], 0, v[82:83]
	v_lshl_add_u64 v[82:83], s[54:55], 2, v[82:83]
	s_lshl_b32 s20, s74, 2
	v_lshl_add_u64 v[82:83], v[82:83], 0, s[20:21]
	global_store_dword v[82:83], v84, off
.LBB0_354:
	s_or_b64 exec, exec, s[56:57]
	v_add_co_u32_e32 v86, vcc, 0x18000, v136
	s_nop 1
	v_addc_co_u32_e32 v87, vcc, 0, v137, vcc
	s_waitcnt lgkmcnt(0)
	s_waitcnt vmcnt(15)
	v_mov_b64_e32 v[82:83], v[174:175]
	v_mov_b64_e32 v[84:85], v[176:177]
	v_lshlrev_b32_e32 v88, 16, v82
	v_and_b32_e32 v89, 0xffff0000, v82
	v_lshlrev_b32_e32 v82, 16, v83
	v_and_b32_e32 v83, 0xffff0000, v83
	v_lshlrev_b32_e32 v90, 16, v84
	v_and_b32_e32 v91, 0xffff0000, v84
	v_lshlrev_b32_e32 v84, 16, v85
	v_and_b32_e32 v85, 0xffff0000, v85
	v_pk_add_f32 v[80:81], v[80:81], v[82:83]
	v_pk_add_f32 v[78:79], v[78:79], v[88:89]
	v_pk_add_f32 v[82:83], v[76:77], v[84:85]
	v_pk_add_f32 v[84:85], v[74:75], v[90:91]
	v_cvt_pk_bf16_f32 v74, v78, v79
	v_cvt_pk_bf16_f32 v75, v80, v81
	v_cvt_pk_bf16_f32 v76, v84, v85
	v_cvt_pk_bf16_f32 v77, v82, v83
	v_mov_b64_e32 v[248:249], v[74:75]
	v_mov_b64_e32 v[250:251], v[76:77]
	s_nop 1
	v_mul_f32_e32 v74, v79, v79
	v_mul_f32_e32 v75, v81, v81
	v_fmac_f32_e32 v74, v78, v78
	v_fmac_f32_e32 v75, v80, v80
	v_add_f32_e32 v74, v74, v75
	v_mul_f32_e32 v75, v85, v85
	v_fmac_f32_e32 v75, v84, v84
	v_add_f32_e32 v74, v75, v74
	v_mul_f32_e32 v75, v83, v83
	v_fmac_f32_e32 v75, v82, v82
	v_add_f32_e32 v82, v75, v74
	s_waitcnt vmcnt(14)
	v_mov_b64_e32 v[74:75], v[178:179]
	v_mov_b64_e32 v[76:77], v[180:181]
	v_lshlrev_b32_e32 v78, 16, v74
	v_and_b32_e32 v79, 0xffff0000, v74
	v_lshlrev_b32_e32 v74, 16, v75
	v_and_b32_e32 v75, 0xffff0000, v75
	v_lshlrev_b32_e32 v80, 16, v76
	v_and_b32_e32 v81, 0xffff0000, v76
	v_lshlrev_b32_e32 v76, 16, v77
	v_and_b32_e32 v77, 0xffff0000, v77
	v_pk_add_f32 v[72:73], v[72:73], v[74:75]
	v_pk_add_f32 v[70:71], v[70:71], v[78:79]
	v_pk_add_f32 v[74:75], v[68:69], v[76:77]
	v_pk_add_f32 v[76:77], v[66:67], v[80:81]
	v_cvt_pk_bf16_f32 v66, v70, v71
	v_cvt_pk_bf16_f32 v67, v72, v73
	v_cvt_pk_bf16_f32 v68, v76, v77
	v_cvt_pk_bf16_f32 v69, v74, v75
	v_mov_b64_e32 v[224:225], v[66:67]
	v_mov_b64_e32 v[228:229], v[68:69]
	v_mov_b32_dpp v66, v248 row_shl:8 row_mask:0xf bank_mask:0x3
	v_mov_b32_dpp v67, v249 row_shl:8 row_mask:0xf bank_mask:0x3
	v_mov_b32_dpp v68, v250 row_shl:8 row_mask:0xf bank_mask:0x3
	v_mov_b32_dpp v69, v251 row_shl:8 row_mask:0xf bank_mask:0x3
	v_mov_b32_dpp v248, v224 row_shr:8 row_mask:0xf bank_mask:0xc
	v_mov_b32_dpp v249, v225 row_shr:8 row_mask:0xf bank_mask:0xc
	v_mov_b32_dpp v250, v228 row_shr:8 row_mask:0xf bank_mask:0xc
	v_mov_b32_dpp v251, v229 row_shr:8 row_mask:0xf bank_mask:0xc
	v_mad_i64_i32 v[224:225], s[98:99], v242, 1, v[86:87]
	v_mad_i64_i32 v[228:229], s[98:99], v243, 1, v[86:87]
	global_store_dwordx4 v[224:225], v[248:251], off
	global_store_dwordx4 v[228:229], v[66:69], off
	s_nop 1
	v_mul_f32_e32 v66, v71, v71
	v_mul_f32_e32 v67, v73, v73
	v_fmac_f32_e32 v66, v70, v70
	v_fmac_f32_e32 v67, v72, v72
	v_add_f32_e32 v66, v66, v67
	v_mul_f32_e32 v67, v77, v77
	v_fmac_f32_e32 v67, v76, v76
	v_add_f32_e32 v66, v67, v66
	v_mul_f32_e32 v67, v75, v75
	v_fmac_f32_e32 v67, v74, v74
	v_add_f32_e32 v66, v67, v66
	v_add_f32_e32 v66, v82, v66
	ds_bpermute_b32 v67, v145, v66
	s_waitcnt lgkmcnt(0)
	v_add_f32_e32 v66, v66, v67
	ds_bpermute_b32 v67, v144, v66
	s_and_saveexec_b64 s[56:57], s[38:39]
	s_cbranch_execz .LBB0_356
	s_waitcnt lgkmcnt(0)
	v_add_f32_e32 v68, v66, v67
	v_or_b32_e32 v66, 48, v138
	v_ashrrev_i32_e32 v67, 31, v66
	v_lshlrev_b64 v[66:67], 6, v[66:67]
	v_lshl_add_u64 v[66:67], s[80:81], 0, v[66:67]
	v_lshl_add_u64 v[66:67], s[54:55], 2, v[66:67]
	s_lshl_b32 s20, s74, 2
	v_lshl_add_u64 v[66:67], v[66:67], 0, s[20:21]
	global_store_dword v[66:67], v68, off
.LBB0_356:
	s_or_b64 exec, exec, s[56:57]
	v_add_co_u32_e32 v70, vcc, 0x40000, v136
	s_nop 1
	v_addc_co_u32_e32 v71, vcc, 0, v137, vcc
	s_waitcnt lgkmcnt(0)
	s_waitcnt vmcnt(15)
	v_mov_b64_e32 v[66:67], v[182:183]
	v_mov_b64_e32 v[68:69], v[184:185]
	v_lshlrev_b32_e32 v72, 16, v66
	v_and_b32_e32 v73, 0xffff0000, v66
	v_lshlrev_b32_e32 v66, 16, v67
	v_and_b32_e32 v67, 0xffff0000, v67
	v_lshlrev_b32_e32 v74, 16, v68
	v_and_b32_e32 v75, 0xffff0000, v68
	v_lshlrev_b32_e32 v68, 16, v69
	v_and_b32_e32 v69, 0xffff0000, v69
	v_pk_add_f32 v[64:65], v[64:65], v[66:67]
	v_pk_add_f32 v[62:63], v[62:63], v[72:73]
	v_pk_add_f32 v[66:67], v[60:61], v[68:69]
	v_pk_add_f32 v[68:69], v[58:59], v[74:75]
	v_cvt_pk_bf16_f32 v58, v62, v63
	v_cvt_pk_bf16_f32 v59, v64, v65
	v_cvt_pk_bf16_f32 v60, v68, v69
	v_cvt_pk_bf16_f32 v61, v66, v67
	v_mov_b64_e32 v[248:249], v[58:59]
	v_mov_b64_e32 v[250:251], v[60:61]
	s_nop 1
	v_mul_f32_e32 v58, v63, v63
	v_mul_f32_e32 v59, v65, v65
	v_fmac_f32_e32 v58, v62, v62
	v_fmac_f32_e32 v59, v64, v64
	v_add_f32_e32 v58, v58, v59
	v_mul_f32_e32 v59, v69, v69
	v_fmac_f32_e32 v59, v68, v68
	v_add_f32_e32 v58, v59, v58
	v_mul_f32_e32 v59, v67, v67
	v_fmac_f32_e32 v59, v66, v66
	v_add_f32_e32 v66, v59, v58
	s_waitcnt vmcnt(14)
; __device__ __forceinline__ unsigned cvt_pk_bf16(float lo, float hi) { f32x2 v = {lo, hi}; bf16x2_t_ b = __builtin_convertvector(v, bf16x2_t_); return __builtin_bit_cast(unsigned, b); }
; __device__ __forceinline__ float bf_lo(unsigned w) { return __uint_as_float(w << 16); }
; __device__ __forceinline__ float bf_hi(unsigned w) { return __uint_as_float(w & 0xffff0000u); }
;     __device__ __forceinline__ void operator()(f32x4 (&acc)[2][2][4][2], const Unit& u, int wr, int wc, int fr, int fq) const {
;         const int t0 = u.pm * 256 + wr * 64 + fr;
;         const int col0 = 256 * u.pn + 32 * wc + 8 * fq;
;         const float* bp0 = first ? ((t0 < NPROMPT) ? xp + (size_t)t0 * 1024 : xs + (size_t)(t0 - NPROMPT) * 1024) : out + (size_t)t0 * 1024;
; #pragma unroll
;         for (int ai = 0; ai < 2; ++ai)
; #pragma unroll
;             for (int m = 0; m < 4; ++m) {
;                 const int j = 128 * ai + 16 * m; float sq = 0.f;
; #pragma unroll
;                 for (int bj = 0; bj < 2; ++bj) {
;                     const size_t o = (size_t)j * 1024 + col0 + 128 * bj;
;                     f32x4 a, b;
;                     if (bb) { const u32x4 w = *(const u32x4*)(xb + (size_t)t0 * 1024 + o);
;                         a = (f32x4){bf_lo(w.x), bf_hi(w.x), bf_lo(w.y), bf_hi(w.y)}; b = (f32x4){bf_lo(w.z), bf_hi(w.z), bf_lo(w.w), bf_hi(w.w)}; }
;                     else { a = *(const f32x4*)(bp0 + o); b = *(const f32x4*)(bp0 + o + 4); }
;                     a = a + acc[ai][bj][m][0]; b = b + acc[ai][bj][m][1];
;                     if (wout) { float* op = out + (size_t)t0 * 1024 + o; *(f32x4*)op = a; *(f32x4*)(op + 4) = b; }
;                     u32x4 w; w.x = cvt_pk_bf16(a.x, a.y); w.y = cvt_pk_bf16(a.z, a.w); w.z = cvt_pk_bf16(b.x, b.y); w.w = cvt_pk_bf16(b.z, b.w);
;                     *(u32x4*)(xb + (size_t)t0 * 1024 + o) = w;
;                     sq += (a.x * a.x + a.y * a.y) + (a.z * a.z + a.w * a.w) + (b.x * b.x + b.y * b.y) + (b.z * b.z + b.w * b.w);
;                 }
;                 sq += __shfl_xor(sq, 16); sq += __shfl_xor(sq, 32);
;                 if (fq == 0) ss[(size_t)(t0 + j) * 16 + 4 * u.pn + wc] = sq;
	v_mov_b64_e32 v[58:59], v[186:187]
	v_mov_b64_e32 v[60:61], v[188:189]
	v_lshlrev_b32_e32 v62, 16, v58
	v_and_b32_e32 v63, 0xffff0000, v58
	v_lshlrev_b32_e32 v58, 16, v59
	v_and_b32_e32 v59, 0xffff0000, v59
	v_lshlrev_b32_e32 v64, 16, v60
	v_and_b32_e32 v65, 0xffff0000, v60
	v_lshlrev_b32_e32 v60, 16, v61
	v_and_b32_e32 v61, 0xffff0000, v61
	v_pk_add_f32 v[56:57], v[56:57], v[58:59]
	v_pk_add_f32 v[54:55], v[54:55], v[62:63]
	v_pk_add_f32 v[58:59], v[52:53], v[60:61]
	v_pk_add_f32 v[60:61], v[50:51], v[64:65]
	v_cvt_pk_bf16_f32 v50, v54, v55
	v_cvt_pk_bf16_f32 v51, v56, v57
	v_cvt_pk_bf16_f32 v52, v60, v61
	v_cvt_pk_bf16_f32 v53, v58, v59
	v_mov_b64_e32 v[224:225], v[50:51]
	v_mov_b64_e32 v[228:229], v[52:53]
	v_mov_b32_dpp v50, v248 row_shl:8 row_mask:0xf bank_mask:0x3
	v_mov_b32_dpp v51, v249 row_shl:8 row_mask:0xf bank_mask:0x3
	v_mov_b32_dpp v52, v250 row_shl:8 row_mask:0xf bank_mask:0x3
	v_mov_b32_dpp v53, v251 row_shl:8 row_mask:0xf bank_mask:0x3
	v_mov_b32_dpp v248, v224 row_shr:8 row_mask:0xf bank_mask:0xc
	v_mov_b32_dpp v249, v225 row_shr:8 row_mask:0xf bank_mask:0xc
	v_mov_b32_dpp v250, v228 row_shr:8 row_mask:0xf bank_mask:0xc
	v_mov_b32_dpp v251, v229 row_shr:8 row_mask:0xf bank_mask:0xc
	v_mad_i64_i32 v[224:225], s[98:99], v242, 1, v[70:71]
	v_mad_i64_i32 v[228:229], s[98:99], v243, 1, v[70:71]
	global_store_dwordx4 v[224:225], v[248:251], off
	global_store_dwordx4 v[228:229], v[50:53], off
	s_nop 1
	v_mul_f32_e32 v50, v55, v55
	v_mul_f32_e32 v51, v57, v57
	v_fmac_f32_e32 v50, v54, v54
	v_fmac_f32_e32 v51, v56, v56
	v_add_f32_e32 v50, v50, v51
	v_mul_f32_e32 v51, v61, v61
	v_fmac_f32_e32 v51, v60, v60
	v_add_f32_e32 v50, v51, v50
	v_mul_f32_e32 v51, v59, v59
	v_fmac_f32_e32 v51, v58, v58
	v_add_f32_e32 v50, v51, v50
	v_add_f32_e32 v50, v66, v50
	ds_bpermute_b32 v51, v145, v50
	s_waitcnt lgkmcnt(0)
	v_add_f32_e32 v50, v50, v51
	ds_bpermute_b32 v51, v144, v50
	s_and_saveexec_b64 s[56:57], s[38:39]
	s_cbranch_execz .LBB0_358
	s_waitcnt lgkmcnt(0)
	v_add_f32_e32 v52, v50, v51
	v_lshl_add_u64 v[50:51], s[54:55], 2, v[114:115]
	s_lshl_b32 s20, s74, 2
	v_lshl_add_u64 v[50:51], v[50:51], 0, s[20:21]
	v_add_co_u32_e32 v50, vcc, 0x2000, v50
	s_nop 1
	v_addc_co_u32_e32 v51, vcc, 0, v51, vcc
	global_store_dword v[50:51], v52, off
.LBB0_358:
	s_or_b64 exec, exec, s[56:57]
	v_add_co_u32_e32 v54, vcc, 0x48000, v136
	s_nop 1
	v_addc_co_u32_e32 v55, vcc, 0, v137, vcc
	s_waitcnt lgkmcnt(0)
	s_waitcnt vmcnt(15)
	v_mov_b64_e32 v[50:51], v[196:197]
	v_mov_b64_e32 v[52:53], v[198:199]
	v_lshlrev_b32_e32 v56, 16, v50
	v_and_b32_e32 v57, 0xffff0000, v50
	v_lshlrev_b32_e32 v50, 16, v51
	v_and_b32_e32 v51, 0xffff0000, v51
	v_lshlrev_b32_e32 v58, 16, v52
	v_and_b32_e32 v59, 0xffff0000, v52
	v_lshlrev_b32_e32 v52, 16, v53
	v_and_b32_e32 v53, 0xffff0000, v53
	v_pk_add_f32 v[48:49], v[48:49], v[50:51]
	v_pk_add_f32 v[46:47], v[46:47], v[56:57]
	v_pk_add_f32 v[50:51], v[44:45], v[52:53]
	v_pk_add_f32 v[52:53], v[42:43], v[58:59]
	v_cvt_pk_bf16_f32 v42, v46, v47
	v_cvt_pk_bf16_f32 v43, v48, v49
	v_cvt_pk_bf16_f32 v44, v52, v53
	v_cvt_pk_bf16_f32 v45, v50, v51
	v_mov_b64_e32 v[248:249], v[42:43]
	v_mov_b64_e32 v[250:251], v[44:45]
	s_nop 1
	v_mul_f32_e32 v42, v47, v47
	v_mul_f32_e32 v43, v49, v49
	v_fmac_f32_e32 v42, v46, v46
	v_fmac_f32_e32 v43, v48, v48
	v_add_f32_e32 v42, v42, v43
	v_mul_f32_e32 v43, v53, v53
	v_fmac_f32_e32 v43, v52, v52
	v_add_f32_e32 v42, v43, v42
	v_mul_f32_e32 v43, v51, v51
	v_fmac_f32_e32 v43, v50, v50
	v_add_f32_e32 v50, v43, v42
	s_waitcnt vmcnt(14)
	v_mov_b64_e32 v[42:43], v[200:201]
	v_mov_b64_e32 v[44:45], v[202:203]
	v_lshlrev_b32_e32 v46, 16, v42
	v_and_b32_e32 v47, 0xffff0000, v42
	v_lshlrev_b32_e32 v42, 16, v43
	v_and_b32_e32 v43, 0xffff0000, v43
	v_lshlrev_b32_e32 v48, 16, v44
	v_and_b32_e32 v49, 0xffff0000, v44
	v_lshlrev_b32_e32 v44, 16, v45
	v_and_b32_e32 v45, 0xffff0000, v45
	v_pk_add_f32 v[40:41], v[40:41], v[42:43]
	v_pk_add_f32 v[38:39], v[38:39], v[46:47]
	v_pk_add_f32 v[42:43], v[36:37], v[44:45]
	v_pk_add_f32 v[44:45], v[34:35], v[48:49]
	v_cvt_pk_bf16_f32 v34, v38, v39
	v_cvt_pk_bf16_f32 v35, v40, v41
	v_cvt_pk_bf16_f32 v36, v44, v45
	v_cvt_pk_bf16_f32 v37, v42, v43
	v_mov_b64_e32 v[224:225], v[34:35]
	v_mov_b64_e32 v[228:229], v[36:37]
	v_mov_b32_dpp v34, v248 row_shl:8 row_mask:0xf bank_mask:0x3
	v_mov_b32_dpp v35, v249 row_shl:8 row_mask:0xf bank_mask:0x3
	v_mov_b32_dpp v36, v250 row_shl:8 row_mask:0xf bank_mask:0x3
	v_mov_b32_dpp v37, v251 row_shl:8 row_mask:0xf bank_mask:0x3
	v_mov_b32_dpp v248, v224 row_shr:8 row_mask:0xf bank_mask:0xc
	v_mov_b32_dpp v249, v225 row_shr:8 row_mask:0xf bank_mask:0xc
	v_mov_b32_dpp v250, v228 row_shr:8 row_mask:0xf bank_mask:0xc
	v_mov_b32_dpp v251, v229 row_shr:8 row_mask:0xf bank_mask:0xc
	v_mad_i64_i32 v[224:225], s[98:99], v242, 1, v[54:55]
	v_mad_i64_i32 v[228:229], s[98:99], v243, 1, v[54:55]
	global_store_dwordx4 v[224:225], v[248:251], off
	global_store_dwordx4 v[228:229], v[34:37], off
	s_nop 1
	v_mul_f32_e32 v34, v39, v39
	v_mul_f32_e32 v35, v41, v41
	v_fmac_f32_e32 v34, v38, v38
	v_fmac_f32_e32 v35, v40, v40
	v_add_f32_e32 v34, v34, v35
	v_mul_f32_e32 v35, v45, v45
	v_fmac_f32_e32 v35, v44, v44
	v_add_f32_e32 v34, v35, v34
	v_mul_f32_e32 v35, v43, v43
	v_fmac_f32_e32 v35, v42, v42
	v_add_f32_e32 v34, v35, v34
	v_add_f32_e32 v34, v50, v34
	ds_bpermute_b32 v35, v145, v34
	s_waitcnt lgkmcnt(0)
	v_add_f32_e32 v34, v34, v35
	ds_bpermute_b32 v35, v144, v34
	s_and_saveexec_b64 s[56:57], s[38:39]
	s_cbranch_execz .LBB0_360
	s_waitcnt lgkmcnt(0)
	v_add_f32_e32 v36, v34, v35
	v_lshl_add_u64 v[34:35], s[54:55], 2, v[114:115]
	s_lshl_b32 s20, s74, 2
	v_lshl_add_u64 v[34:35], v[34:35], 0, s[20:21]
	v_add_co_u32_e32 v34, vcc, 0x2000, v34
	s_nop 1
	v_addc_co_u32_e32 v35, vcc, 0, v35, vcc
	global_store_dword v[34:35], v36, off offset:1024
; __device__ __forceinline__ unsigned cvt_pk_bf16(float lo, float hi) { f32x2 v = {lo, hi}; bf16x2_t_ b = __builtin_convertvector(v, bf16x2_t_); return __builtin_bit_cast(unsigned, b); }
; __device__ __forceinline__ float bf_lo(unsigned w) { return __uint_as_float(w << 16); }
; __device__ __forceinline__ float bf_hi(unsigned w) { return __uint_as_float(w & 0xffff0000u); }
;     __device__ __forceinline__ void operator()(f32x4 (&acc)[2][2][4][2], const Unit& u, int wr, int wc, int fr, int fq) const {
;         const int t0 = u.pm * 256 + wr * 64 + fr;
;         const int col0 = 256 * u.pn + 32 * wc + 8 * fq;
;         const float* bp0 = first ? ((t0 < NPROMPT) ? xp + (size_t)t0 * 1024 : xs + (size_t)(t0 - NPROMPT) * 1024) : out + (size_t)t0 * 1024;
; #pragma unroll
;         for (int ai = 0; ai < 2; ++ai)
; #pragma unroll
;             for (int m = 0; m < 4; ++m) {
;                 const int j = 128 * ai + 16 * m; float sq = 0.f;
; #pragma unroll
;                 for (int bj = 0; bj < 2; ++bj) {
;                     const size_t o = (size_t)j * 1024 + col0 + 128 * bj;
;                     f32x4 a, b;
;                     if (bb) { const u32x4 w = *(const u32x4*)(xb + (size_t)t0 * 1024 + o);
;                         a = (f32x4){bf_lo(w.x), bf_hi(w.x), bf_lo(w.y), bf_hi(w.y)}; b = (f32x4){bf_lo(w.z), bf_hi(w.z), bf_lo(w.w), bf_hi(w.w)}; }
;                     else { a = *(const f32x4*)(bp0 + o); b = *(const f32x4*)(bp0 + o + 4); }
;                     a = a + acc[ai][bj][m][0]; b = b + acc[ai][bj][m][1];
;                     if (wout) { float* op = out + (size_t)t0 * 1024 + o; *(f32x4*)op = a; *(f32x4*)(op + 4) = b; }
;                     u32x4 w; w.x = cvt_pk_bf16(a.x, a.y); w.y = cvt_pk_bf16(a.z, a.w); w.z = cvt_pk_bf16(b.x, b.y); w.w = cvt_pk_bf16(b.z, b.w);
;                     *(u32x4*)(xb + (size_t)t0 * 1024 + o) = w;
;                     sq += (a.x * a.x + a.y * a.y) + (a.z * a.z + a.w * a.w) + (b.x * b.x + b.y * b.y) + (b.z * b.z + b.w * b.w);
;                 }
;                 sq += __shfl_xor(sq, 16); sq += __shfl_xor(sq, 32);
;                 if (fq == 0) ss[(size_t)(t0 + j) * 16 + 4 * u.pn + wc] = sq;
.LBB0_360:
	s_or_b64 exec, exec, s[56:57]
	v_add_co_u32_e32 v38, vcc, 0x50000, v136
	s_nop 1
	v_addc_co_u32_e32 v39, vcc, 0, v137, vcc
	s_waitcnt lgkmcnt(0)
	s_waitcnt vmcnt(15)
	v_mov_b64_e32 v[34:35], v[204:205]
	v_mov_b64_e32 v[36:37], v[206:207]
	v_lshlrev_b32_e32 v40, 16, v34
	v_and_b32_e32 v41, 0xffff0000, v34
	v_lshlrev_b32_e32 v34, 16, v35
	v_and_b32_e32 v35, 0xffff0000, v35
	v_lshlrev_b32_e32 v42, 16, v36
	v_and_b32_e32 v43, 0xffff0000, v36
	v_lshlrev_b32_e32 v36, 16, v37
	v_and_b32_e32 v37, 0xffff0000, v37
	v_pk_add_f32 v[32:33], v[32:33], v[34:35]
	v_pk_add_f32 v[30:31], v[30:31], v[40:41]
	v_pk_add_f32 v[34:35], v[28:29], v[36:37]
	v_pk_add_f32 v[36:37], v[26:27], v[42:43]
	v_cvt_pk_bf16_f32 v26, v30, v31
	v_cvt_pk_bf16_f32 v27, v32, v33
	v_cvt_pk_bf16_f32 v28, v36, v37
	v_cvt_pk_bf16_f32 v29, v34, v35
	v_mov_b64_e32 v[248:249], v[26:27]
	v_mov_b64_e32 v[250:251], v[28:29]
	s_nop 1
	v_mul_f32_e32 v26, v31, v31
	v_mul_f32_e32 v27, v33, v33
	v_fmac_f32_e32 v26, v30, v30
	v_fmac_f32_e32 v27, v32, v32
	v_add_f32_e32 v26, v26, v27
	v_mul_f32_e32 v27, v37, v37
	v_fmac_f32_e32 v27, v36, v36
	v_add_f32_e32 v26, v27, v26
	v_mul_f32_e32 v27, v35, v35
	v_fmac_f32_e32 v27, v34, v34
	v_add_f32_e32 v34, v27, v26
	s_waitcnt vmcnt(14)
	v_mov_b64_e32 v[26:27], v[208:209]
	v_mov_b64_e32 v[28:29], v[210:211]
	v_lshlrev_b32_e32 v30, 16, v26
	v_and_b32_e32 v31, 0xffff0000, v26
	v_lshlrev_b32_e32 v26, 16, v27
	v_and_b32_e32 v27, 0xffff0000, v27
	v_lshlrev_b32_e32 v32, 16, v28
	v_and_b32_e32 v33, 0xffff0000, v28
	v_lshlrev_b32_e32 v28, 16, v29
	v_and_b32_e32 v29, 0xffff0000, v29
	v_pk_add_f32 v[24:25], v[24:25], v[26:27]
	v_pk_add_f32 v[22:23], v[22:23], v[30:31]
	v_pk_add_f32 v[26:27], v[20:21], v[28:29]
	v_pk_add_f32 v[28:29], v[18:19], v[32:33]
	v_cvt_pk_bf16_f32 v18, v22, v23
	v_cvt_pk_bf16_f32 v19, v24, v25
	v_cvt_pk_bf16_f32 v20, v28, v29
	v_cvt_pk_bf16_f32 v21, v26, v27
	v_mov_b64_e32 v[224:225], v[18:19]
	v_mov_b64_e32 v[228:229], v[20:21]
	v_mov_b32_dpp v18, v248 row_shl:8 row_mask:0xf bank_mask:0x3
	v_mov_b32_dpp v19, v249 row_shl:8 row_mask:0xf bank_mask:0x3
	v_mov_b32_dpp v20, v250 row_shl:8 row_mask:0xf bank_mask:0x3
	v_mov_b32_dpp v21, v251 row_shl:8 row_mask:0xf bank_mask:0x3
	v_mov_b32_dpp v248, v224 row_shr:8 row_mask:0xf bank_mask:0xc
	v_mov_b32_dpp v249, v225 row_shr:8 row_mask:0xf bank_mask:0xc
	v_mov_b32_dpp v250, v228 row_shr:8 row_mask:0xf bank_mask:0xc
	v_mov_b32_dpp v251, v229 row_shr:8 row_mask:0xf bank_mask:0xc
	v_mad_i64_i32 v[224:225], s[98:99], v242, 1, v[38:39]
	v_mad_i64_i32 v[228:229], s[98:99], v243, 1, v[38:39]
	global_store_dwordx4 v[224:225], v[248:251], off
	global_store_dwordx4 v[228:229], v[18:21], off
	s_nop 1
	v_mul_f32_e32 v18, v23, v23
	v_mul_f32_e32 v19, v25, v25
	v_fmac_f32_e32 v18, v22, v22
	v_fmac_f32_e32 v19, v24, v24
	v_add_f32_e32 v18, v18, v19
	v_mul_f32_e32 v19, v29, v29
	v_fmac_f32_e32 v19, v28, v28
	v_add_f32_e32 v18, v19, v18
	v_mul_f32_e32 v19, v27, v27
	v_fmac_f32_e32 v19, v26, v26
	v_add_f32_e32 v18, v19, v18
	v_add_f32_e32 v18, v34, v18
	ds_bpermute_b32 v19, v145, v18
	s_waitcnt lgkmcnt(0)
	v_add_f32_e32 v18, v18, v19
	ds_bpermute_b32 v19, v144, v18
	s_and_saveexec_b64 s[56:57], s[38:39]
	s_cbranch_execz .LBB0_362
	s_waitcnt lgkmcnt(0)
	v_add_f32_e32 v20, v18, v19
	v_lshl_add_u64 v[18:19], s[54:55], 2, v[114:115]
	s_lshl_b32 s20, s74, 2
	v_lshl_add_u64 v[18:19], v[18:19], 0, s[20:21]
	v_add_co_u32_e32 v18, vcc, 0x2000, v18
	s_nop 1
	v_addc_co_u32_e32 v19, vcc, 0, v19, vcc
	global_store_dword v[18:19], v20, off offset:2048
.LBB0_362:
	s_or_b64 exec, exec, s[56:57]
	v_add_co_u32_e32 v22, vcc, 0x58000, v136
	s_nop 1
	v_addc_co_u32_e32 v23, vcc, 0, v137, vcc
	s_waitcnt lgkmcnt(0)
	s_waitcnt vmcnt(15)
	v_mov_b64_e32 v[18:19], v[212:213]
	v_mov_b64_e32 v[20:21], v[214:215]
	v_lshlrev_b32_e32 v24, 16, v18
	v_and_b32_e32 v25, 0xffff0000, v18
	v_lshlrev_b32_e32 v18, 16, v19
	v_and_b32_e32 v19, 0xffff0000, v19
	v_lshlrev_b32_e32 v26, 16, v20
	v_and_b32_e32 v27, 0xffff0000, v20
	v_lshlrev_b32_e32 v20, 16, v21
	v_and_b32_e32 v21, 0xffff0000, v21
	v_pk_add_f32 v[16:17], v[16:17], v[18:19]
	v_pk_add_f32 v[14:15], v[14:15], v[24:25]
	v_pk_add_f32 v[18:19], v[12:13], v[20:21]
	v_pk_add_f32 v[20:21], v[10:11], v[26:27]
	v_cvt_pk_bf16_f32 v10, v14, v15
	v_cvt_pk_bf16_f32 v11, v16, v17
	v_cvt_pk_bf16_f32 v12, v20, v21
	v_cvt_pk_bf16_f32 v13, v18, v19
	v_mov_b64_e32 v[248:249], v[10:11]
	v_mov_b64_e32 v[250:251], v[12:13]
	s_nop 1
	v_mul_f32_e32 v10, v15, v15
	v_mul_f32_e32 v11, v17, v17
	v_fmac_f32_e32 v10, v14, v14
	v_fmac_f32_e32 v11, v16, v16
	v_add_f32_e32 v10, v10, v11
	v_mul_f32_e32 v11, v21, v21
	v_fmac_f32_e32 v11, v20, v20
	v_add_f32_e32 v10, v11, v10
	v_mul_f32_e32 v11, v19, v19
	v_fmac_f32_e32 v11, v18, v18
	v_add_f32_e32 v18, v11, v10
	s_waitcnt vmcnt(14)
	v_mov_b64_e32 v[10:11], v[236:237]
	v_mov_b64_e32 v[12:13], v[238:239]
	v_lshlrev_b32_e32 v14, 16, v10
	v_and_b32_e32 v15, 0xffff0000, v10
	v_lshlrev_b32_e32 v10, 16, v11
	v_and_b32_e32 v11, 0xffff0000, v11
	v_lshlrev_b32_e32 v16, 16, v12
	v_and_b32_e32 v17, 0xffff0000, v12
	v_lshlrev_b32_e32 v12, 16, v13
	v_and_b32_e32 v13, 0xffff0000, v13
	v_pk_add_f32 v[8:9], v[8:9], v[10:11]
	v_pk_add_f32 v[6:7], v[6:7], v[14:15]
	v_pk_add_f32 v[10:11], v[4:5], v[12:13]
	v_pk_add_f32 v[12:13], v[2:3], v[16:17]
	v_cvt_pk_bf16_f32 v2, v6, v7
	v_cvt_pk_bf16_f32 v3, v8, v9
	v_cvt_pk_bf16_f32 v4, v12, v13
	v_cvt_pk_bf16_f32 v5, v10, v11
	v_mov_b64_e32 v[224:225], v[2:3]
	v_mov_b64_e32 v[228:229], v[4:5]
	v_mov_b32_dpp v2, v248 row_shl:8 row_mask:0xf bank_mask:0x3
	v_mov_b32_dpp v3, v249 row_shl:8 row_mask:0xf bank_mask:0x3
	v_mov_b32_dpp v4, v250 row_shl:8 row_mask:0xf bank_mask:0x3
	v_mov_b32_dpp v5, v251 row_shl:8 row_mask:0xf bank_mask:0x3
	v_mov_b32_dpp v248, v224 row_shr:8 row_mask:0xf bank_mask:0xc
	v_mov_b32_dpp v249, v225 row_shr:8 row_mask:0xf bank_mask:0xc
	v_mov_b32_dpp v250, v228 row_shr:8 row_mask:0xf bank_mask:0xc
	v_mov_b32_dpp v251, v229 row_shr:8 row_mask:0xf bank_mask:0xc
	v_mad_i64_i32 v[224:225], s[98:99], v242, 1, v[22:23]
	v_mad_i64_i32 v[228:229], s[98:99], v243, 1, v[22:23]
	global_store_dwordx4 v[224:225], v[248:251], off
	global_store_dwordx4 v[228:229], v[2:5], off
	s_nop 1
	v_mul_f32_e32 v2, v7, v7
	v_mul_f32_e32 v3, v9, v9
	v_fmac_f32_e32 v2, v6, v6
	v_fmac_f32_e32 v3, v8, v8
	v_add_f32_e32 v2, v2, v3
	v_mul_f32_e32 v3, v13, v13
	v_fmac_f32_e32 v3, v12, v12
	v_add_f32_e32 v2, v3, v2
	v_mul_f32_e32 v3, v11, v11
	v_fmac_f32_e32 v3, v10, v10
	v_add_f32_e32 v2, v3, v2
	v_add_f32_e32 v2, v18, v2
	ds_bpermute_b32 v3, v145, v2
	s_waitcnt lgkmcnt(0)
	v_add_f32_e32 v2, v2, v3
	ds_bpermute_b32 v3, v144, v2
	s_and_saveexec_b64 s[56:57], s[38:39]
	s_cbranch_execz .LBB0_364
	s_waitcnt lgkmcnt(0)
	v_add_f32_e32 v4, v2, v3
	v_lshl_add_u64 v[2:3], s[54:55], 2, v[114:115]
	s_lshl_b32 s20, s74, 2
	v_lshl_add_u64 v[2:3], v[2:3], 0, s[20:21]
	v_add_co_u32_e32 v2, vcc, 0x2000, v2
	s_nop 1
	v_addc_co_u32_e32 v3, vcc, 0, v3, vcc
	global_store_dword v[2:3], v4, off offset:3072
